# attention (S4): one static s_setprio 1 for waves 4-7 at phase start, per-segment priority flips in the attention loops removed
# baseline (speedup 1.0000x reference)
.LBB0_746:
	v_readlane_b32 s98, v254, 56
	s_nop 3
	s_cmp_lt_u32 s98, 4
	s_cbranch_scc1 .Lap_skip
	s_setprio 1

.LBB0_907:
	v_and_b32_e32 v197, 31, v181
	v_lshlrev_b32_e32 v18, 3, v197
	v_add_u32_e32 v0, 0, v18
	v_add_u32_e32 v213, 0x10800, v0
	v_ashrrev_i32_e32 v208, 5, v181
	s_add_i32 s42, s24, s58
	ds_read2_b64 v[20:23], v213 offset1:32
	v_mov_b64_e32 v[26:27], s[10:11]
	v_mov_b64_e32 v[0:1], s[8:9]
	v_mov_b64_e32 v[24:25], s[8:9]
	v_mov_b64_e32 v[2:3], s[10:11]
	s_waitcnt lgkmcnt(0)
	v_or_b32_e32 v1, 1.0, v21
	v_mov_b32_e32 v0, v20
	v_or_b32_e32 v25, 1.0, v23
	v_mov_b32_e32 v24, v22
	v_cmp_gt_u32_e64 s[6:7], 32, v181
	v_mov_b32_e32 v130, s11
	s_nop 0
	v_cndmask_b32_e64 v128, 0, v204, s[6:7]
	v_cndmask_b32_e64 v129, 0, v191, s[6:7]
	s_nop 1
	v_mfma_f32_32x32x16_bf16 v[0:15], v[0:3], v[128:131], 0
	v_mfma_f32_32x32x16_bf16 v[64:79], v[24:27], v[128:131], 0
	v_lshlrev_b32_e32 v19, 4, v181
	v_lshlrev_b32_e32 v25, 4, v208
	v_and_b32_e32 v26, 0x70, v19
	v_lshlrev_b32_e32 v24, 8, v197
	v_xad_u32 v20, v26, v25, 0
	v_add_u32_e32 v212, v20, v24
	ds_read_b128 v[20:23], v212 offset:32768
	v_add_u32_e32 v27, 32, v25
	v_xad_u32 v27, v27, v26, 0
	v_add_u32_e32 v211, v27, v24
	v_add_u32_e32 v27, 64, v25
	v_xad_u32 v27, v27, v26, 0
	v_add_u32_e32 v210, v27, v24
	s_waitcnt lgkmcnt(0)
	v_mfma_f32_32x32x16_bf16 v[0:15], v[20:23], v[160:163], v[0:15]
	ds_read_b128 v[20:23], v212 offset:40960
	v_add_u32_e32 v25, 0x60, v25
	v_xad_u32 v25, v25, v26, 0
	v_add_u32_e32 v209, v25, v24
	s_waitcnt lgkmcnt(0)
	v_mfma_f32_32x32x16_bf16 v[64:79], v[20:23], v[160:163], v[64:79]
	ds_read_b128 v[20:23], v211 offset:32768
	s_waitcnt lgkmcnt(0)
	v_mfma_f32_32x32x16_bf16 v[0:15], v[20:23], v[156:159], v[0:15]
	ds_read_b128 v[20:23], v211 offset:40960
	s_waitcnt lgkmcnt(0)
	v_mfma_f32_32x32x16_bf16 v[64:79], v[20:23], v[156:159], v[64:79]
	ds_read_b128 v[20:23], v210 offset:32768
	s_waitcnt lgkmcnt(0)
	v_mfma_f32_32x32x16_bf16 v[0:15], v[20:23], v[152:155], v[0:15]
	ds_read_b128 v[20:23], v210 offset:40960
	s_waitcnt lgkmcnt(0)
	v_mfma_f32_32x32x16_bf16 v[64:79], v[20:23], v[152:155], v[64:79]
	ds_read_b128 v[20:23], v209 offset:32768
	s_waitcnt lgkmcnt(0)
	v_mfma_f32_32x32x16_bf16 v[0:15], v[20:23], v[148:151], v[0:15]
	ds_read_b128 v[20:23], v209 offset:40960
	s_waitcnt lgkmcnt(0)
	v_mfma_f32_32x32x16_bf16 v[64:79], v[20:23], v[148:151], v[64:79]
	ds_read_b128 v[20:23], v212 offset:32896
	s_waitcnt lgkmcnt(0)
	v_mfma_f32_32x32x16_bf16 v[0:15], v[20:23], v[144:147], v[0:15]
	ds_read_b128 v[20:23], v212 offset:41088
	s_waitcnt lgkmcnt(0)
	v_mfma_f32_32x32x16_bf16 v[64:79], v[20:23], v[144:147], v[64:79]
	ds_read_b128 v[20:23], v211 offset:32896
	s_waitcnt lgkmcnt(0)
	v_mfma_f32_32x32x16_bf16 v[0:15], v[20:23], v[136:139], v[0:15]
	ds_read_b128 v[20:23], v211 offset:41088
	s_waitcnt lgkmcnt(0)
	v_mfma_f32_32x32x16_bf16 v[64:79], v[20:23], v[136:139], v[64:79]
	ds_read_b128 v[20:23], v210 offset:32896
	s_waitcnt lgkmcnt(0)
	v_mfma_f32_32x32x16_bf16 v[0:15], v[20:23], v[140:143], v[0:15]
	ds_read_b128 v[20:23], v210 offset:41088
	s_waitcnt lgkmcnt(0)
	v_mfma_f32_32x32x16_bf16 v[64:79], v[20:23], v[140:143], v[64:79]
	ds_read_b128 v[20:23], v209 offset:32896
	s_waitcnt lgkmcnt(0)
	v_mfma_f32_32x32x16_bf16 v[0:15], v[20:23], v[132:135], v[0:15]
	ds_read_b128 v[20:23], v209 offset:41088
	s_waitcnt lgkmcnt(0)
	v_mfma_f32_32x32x16_bf16 v[64:79], v[20:23], v[132:135], v[64:79]
	s_or_b32 s16, s3, 63
	s_cmp_gt_i32 s16, s42
	s_cselect_b64 s[16:17], -1, 0
	s_and_b64 vcc, exec, s[16:17]
	s_cbranch_vccnz .LBB0_909
	s_sub_i32 s16, s42, s29
	s_add_i32 s16, s16, 31
	s_cmp_le_i32 s3, s16
	s_cselect_b64 s[16:17], -1, 0

.LBB0_919:
	s_waitcnt vmcnt(0)
	v_add_u32_e32 v112, s74, v205
	v_add_u32_e32 v80, 1, v112
	v_ashrrev_i32_e32 v81, 31, v80
	v_add_u32_e32 v84, 33, v112
	v_lshlrev_b64 v[80:81], 8, v[80:81]
	v_ashrrev_i32_e32 v85, 31, v84
	v_lshl_add_u64 v[82:83], v[186:187], 0, v[80:81]
	v_lshlrev_b64 v[84:85], 8, v[84:85]
	v_lshl_add_u64 v[80:81], v[188:189], 0, v[80:81]
	v_lshl_add_u64 v[86:87], v[186:187], 0, v[84:85]
	global_load_dwordx4 v[164:167], v[82:83], off
	global_load_dwordx4 v[168:171], v[86:87], off
	v_lshl_add_u64 v[82:83], v[188:189], 0, v[84:85]
	global_load_dwordx4 v[172:175], v[80:81], off
	global_load_dwordx4 v[176:179], v[82:83], off
	ds_read2_b64 v[94:97], v185 offset1:32
	v_mov_b64_e32 v[82:83], s[10:11]
	v_mov_b64_e32 v[100:101], s[10:11]
	v_mov_b64_e32 v[80:81], s[8:9]
	v_mov_b64_e32 v[98:99], s[8:9]
	s_waitcnt lgkmcnt(0)
	v_or_b32_e32 v81, 1.0, v95
	v_mov_b32_e32 v80, v94
	v_or_b32_e32 v99, 1.0, v97
	v_mov_b32_e32 v98, v96
	v_cndmask_b32_e64 v129, 0, v218, s[6:7]
	v_cndmask_b32_e64 v130, 0, v219, s[6:7]
	s_nop 1
	v_mfma_f32_32x32x16_bf16 v[80:95], v[80:83], v[128:131], 0
	v_mfma_f32_32x32x16_bf16 v[96:111], v[98:101], v[128:131], 0
	ds_read_b128 v[114:117], v212 offset:49152
	ds_read_b128 v[118:121], v212 offset:57344
	ds_read_b128 v[122:125], v211 offset:49152
	s_waitcnt lgkmcnt(2)
	v_mfma_f32_32x32x16_bf16 v[80:95], v[114:117], v[160:163], v[80:95]
	ds_read_b128 v[114:117], v211 offset:57344
	s_waitcnt lgkmcnt(2)
	v_mfma_f32_32x32x16_bf16 v[96:111], v[118:121], v[160:163], v[96:111]
	ds_read_b128 v[118:121], v210 offset:49152
	s_waitcnt lgkmcnt(2)
	v_mfma_f32_32x32x16_bf16 v[80:95], v[122:125], v[156:159], v[80:95]
	ds_read_b128 v[122:125], v210 offset:57344
	s_waitcnt lgkmcnt(2)
	v_mfma_f32_32x32x16_bf16 v[96:111], v[114:117], v[156:159], v[96:111]
	ds_read_b128 v[114:117], v209 offset:49152
	s_waitcnt lgkmcnt(2)
	v_mfma_f32_32x32x16_bf16 v[80:95], v[118:121], v[152:155], v[80:95]
	ds_read_b128 v[118:121], v209 offset:57344
	s_waitcnt lgkmcnt(2)
	v_mfma_f32_32x32x16_bf16 v[96:111], v[122:125], v[152:155], v[96:111]
	ds_read_b128 v[122:125], v212 offset:49280
	s_waitcnt lgkmcnt(2)
	v_mfma_f32_32x32x16_bf16 v[80:95], v[114:117], v[148:151], v[80:95]
	ds_read_b128 v[114:117], v212 offset:57472
	s_waitcnt lgkmcnt(2)
	v_mfma_f32_32x32x16_bf16 v[96:111], v[118:121], v[148:151], v[96:111]
	ds_read_b128 v[118:121], v211 offset:49280
	s_waitcnt lgkmcnt(2)
	v_mfma_f32_32x32x16_bf16 v[80:95], v[122:125], v[144:147], v[80:95]
	ds_read_b128 v[122:125], v211 offset:57472
	s_waitcnt lgkmcnt(2)
	v_mfma_f32_32x32x16_bf16 v[96:111], v[114:117], v[144:147], v[96:111]
	ds_read_b128 v[114:117], v210 offset:49280
	s_waitcnt lgkmcnt(2)
	v_mfma_f32_32x32x16_bf16 v[80:95], v[118:121], v[136:139], v[80:95]
	ds_read_b128 v[118:121], v210 offset:57472
	s_waitcnt lgkmcnt(2)
	v_mfma_f32_32x32x16_bf16 v[96:111], v[122:125], v[136:139], v[96:111]
	ds_read_b128 v[122:125], v209 offset:49280
	s_waitcnt lgkmcnt(2)
	v_mfma_f32_32x32x16_bf16 v[80:95], v[114:117], v[140:143], v[80:95]
	ds_read_b128 v[114:117], v209 offset:57472
	s_waitcnt lgkmcnt(2)
	v_mfma_f32_32x32x16_bf16 v[96:111], v[118:121], v[140:143], v[96:111]
	s_waitcnt lgkmcnt(1)
	v_mfma_f32_32x32x16_bf16 v[80:95], v[122:125], v[132:135], v[80:95]
	s_waitcnt lgkmcnt(0)
	v_mfma_f32_32x32x16_bf16 v[96:111], v[114:117], v[132:135], v[96:111]
	v_exp_f32_e32 v113, v64
	v_add_f32_e32 v64, 0, v237
	v_add_f32_e32 v64, v239, v64
	v_add_f32_e32 v64, v235, v64
	v_add_f32_e32 v64, v238, v64
	v_add_f32_e32 v64, v233, v64
	v_add_f32_e32 v64, v236, v64
	v_add_f32_e32 v64, v232, v64
	v_add_f32_e32 v64, v234, v64
	v_add_f32_e32 v64, v229, v64
	v_add_f32_e32 v64, v231, v64
	v_add_f32_e32 v64, v227, v64
	v_add_f32_e32 v64, v230, v64
	v_add_f32_e32 v64, v225, v64
	v_exp_f32_e32 v114, v65
	v_add_f32_e32 v64, v228, v64
	v_exp_f32_e32 v115, v66
	v_add_f32_e32 v64, v224, v64
	v_exp_f32_e32 v116, v67
	v_add_f32_e32 v64, v226, v64
	v_exp_f32_e32 v117, v68
	v_add_f32_e32 v64, v113, v64
	v_exp_f32_e32 v118, v69
	v_add_f32_e32 v64, v114, v64
	v_exp_f32_e32 v119, v70
	v_add_f32_e32 v64, v115, v64
	v_exp_f32_e32 v120, v71
	v_add_f32_e32 v64, v116, v64
	v_exp_f32_e32 v121, v72
	v_add_f32_e32 v64, v117, v64
	v_exp_f32_e32 v122, v73
	v_add_f32_e32 v64, v118, v64
	v_exp_f32_e32 v123, v74
	v_add_f32_e32 v64, v119, v64
	v_exp_f32_e32 v124, v75
	v_add_f32_e32 v64, v120, v64
	v_exp_f32_e32 v125, v76
	v_add_f32_e32 v64, v121, v64
	v_exp_f32_e32 v126, v77
	v_add_f32_e32 v64, v122, v64
	v_exp_f32_e32 v127, v78
	v_add_f32_e32 v64, v123, v64
	v_exp_f32_e32 v79, v79
	v_add_f32_e32 v64, v124, v64
	v_add_f32_e32 v64, v125, v64
	v_add_f32_e32 v64, v126, v64
	v_add_f32_e32 v64, v127, v64
	v_add_f32_e32 v221, v79, v64
	v_mov_b32_e32 v222, v221
	s_nop 1
	v_permlane32_swap_b32_e32 v221, v222
	v_cvt_pk_bf16_f32 v64, v237, v239
	v_cvt_pk_bf16_f32 v65, v235, v238
	v_cvt_pk_bf16_f32 v66, v233, v236
	v_cvt_pk_bf16_f32 v67, v232, v234
	v_cvt_pk_bf16_f32 v68, v229, v231
	v_cvt_pk_bf16_f32 v69, v227, v230
	v_cvt_pk_bf16_f32 v70, v225, v228
	v_cvt_pk_bf16_f32 v71, v224, v226
	v_cvt_pk_bf16_f32 v72, v113, v114
	v_cvt_pk_bf16_f32 v73, v115, v116
	v_cvt_pk_bf16_f32 v74, v117, v118
	v_cvt_pk_bf16_f32 v75, v119, v120
	v_cvt_pk_bf16_f32 v76, v121, v122
	v_cvt_pk_bf16_f32 v77, v123, v124
	v_cvt_pk_bf16_f32 v78, v125, v126
	v_cvt_pk_bf16_f32 v79, v127, v79
	s_nop 0
	v_permlane32_swap_b32_e32 v64, v66
	v_permlane32_swap_b32_e32 v65, v67
	v_permlane32_swap_b32_e32 v68, v70
	v_permlane32_swap_b32_e32 v69, v71
	v_permlane32_swap_b32_e32 v72, v74
	v_permlane32_swap_b32_e32 v73, v75
	v_permlane32_swap_b32_e32 v76, v78
	v_permlane32_swap_b32_e32 v77, v79
	ds_read_b64_tr_b16 v[114:115], v203 offset:0
	ds_read_b64_tr_b16 v[116:117], v203 offset:0x800
	ds_read_b64_tr_b16 v[118:119], v203 offset:0x1000
	ds_read_b64_tr_b16 v[120:121], v203 offset:0x1800
	ds_read_b64_tr_b16 v[122:123], v203 offset:0x2000
	ds_read_b64_tr_b16 v[124:125], v203 offset:0x2800
	ds_read_b64_tr_b16 v[224:225], v203 offset:0x3000
	ds_read_b64_tr_b16 v[226:227], v203 offset:0x3800
	s_waitcnt lgkmcnt(0)
	s_nop 0
	v_mfma_f32_32x32x16_bf16 v[48:63], v[64:67], v[114:117], v[48:63]
	ds_read_b64_tr_b16 v[114:115], v203 offset:0x200
	ds_read_b64_tr_b16 v[116:117], v203 offset:0xa00
	v_mfma_f32_32x32x16_bf16 v[48:63], v[68:71], v[118:121], v[48:63]
	ds_read_b64_tr_b16 v[118:119], v203 offset:0x1200
	ds_read_b64_tr_b16 v[120:121], v203 offset:0x1a00
	v_mfma_f32_32x32x16_bf16 v[48:63], v[72:75], v[122:125], v[48:63]
	ds_read_b64_tr_b16 v[122:123], v203 offset:0x2200
	ds_read_b64_tr_b16 v[124:125], v203 offset:0x2a00
	v_mfma_f32_32x32x16_bf16 v[48:63], v[76:79], v[224:227], v[48:63]
	ds_read_b64_tr_b16 v[224:225], v203 offset:0x3200
	ds_read_b64_tr_b16 v[226:227], v203 offset:0x3a00
	s_waitcnt lgkmcnt(0)
	v_mfma_f32_32x32x16_bf16 v[32:47], v[64:67], v[114:117], v[32:47]
	ds_read_b64_tr_b16 v[114:115], v203 offset:0x400
	ds_read_b64_tr_b16 v[116:117], v203 offset:0xc00
	v_mfma_f32_32x32x16_bf16 v[32:47], v[68:71], v[118:121], v[32:47]
	ds_read_b64_tr_b16 v[118:119], v203 offset:0x1400
	ds_read_b64_tr_b16 v[120:121], v203 offset:0x1c00
	v_mfma_f32_32x32x16_bf16 v[32:47], v[72:75], v[122:125], v[32:47]
	ds_read_b64_tr_b16 v[122:123], v203 offset:0x2400
	ds_read_b64_tr_b16 v[124:125], v203 offset:0x2c00
	v_mfma_f32_32x32x16_bf16 v[32:47], v[76:79], v[224:227], v[32:47]
	ds_read_b64_tr_b16 v[224:225], v203 offset:0x3400
	ds_read_b64_tr_b16 v[226:227], v203 offset:0x3c00
	s_waitcnt lgkmcnt(0)
	v_mfma_f32_32x32x16_bf16 v[16:31], v[64:67], v[114:117], v[16:31]
	ds_read_b64_tr_b16 v[114:115], v203 offset:0x600
	ds_read_b64_tr_b16 v[116:117], v203 offset:0xe00
	v_mfma_f32_32x32x16_bf16 v[16:31], v[68:71], v[118:121], v[16:31]
	ds_read_b64_tr_b16 v[118:119], v203 offset:0x1600
	ds_read_b64_tr_b16 v[120:121], v203 offset:0x1e00
	v_mfma_f32_32x32x16_bf16 v[16:31], v[72:75], v[122:125], v[16:31]
	ds_read_b64_tr_b16 v[122:123], v203 offset:0x2600
	ds_read_b64_tr_b16 v[124:125], v203 offset:0x2e00
	v_mfma_f32_32x32x16_bf16 v[16:31], v[76:79], v[224:227], v[16:31]
	ds_read_b64_tr_b16 v[224:225], v203 offset:0x3600
	ds_read_b64_tr_b16 v[226:227], v203 offset:0x3e00
	s_waitcnt lgkmcnt(0)
	v_mfma_f32_32x32x16_bf16 v[0:15], v[64:67], v[114:117], v[0:15]
	v_mfma_f32_32x32x16_bf16 v[0:15], v[68:71], v[118:121], v[0:15]
	v_mfma_f32_32x32x16_bf16 v[0:15], v[72:75], v[122:125], v[0:15]
	v_mfma_f32_32x32x16_bf16 v[0:15], v[76:79], v[224:227], v[0:15]
	s_sub_i32 s3, s74, 63
	s_cmp_le_i32 s74, s42
	s_cselect_b64 s[4:5], -1, 0
	s_cmp_gt_i32 s3, s16
	s_cselect_b64 s[36:37], -1, 0
	s_and_b64 s[4:5], s[4:5], s[36:37]
	s_and_b64 vcc, exec, s[4:5]
	s_cbranch_vccnz .LBB0_921
	v_add_u32_e32 v64, 0x7b, v220
	v_cmp_gt_u32_e32 vcc, s29, v64
	v_add_u32_e32 v64, 0x5b, v220
	s_nop 0
	v_cndmask_b32_e32 v80, v196, v80, vcc
	v_cmp_gt_u32_e32 vcc, s29, v64
	v_add_u32_e32 v64, 0x7a, v220
	s_nop 0
	v_cndmask_b32_e32 v96, v196, v96, vcc
	v_cmp_gt_u32_e32 vcc, s29, v64
	v_add_u32_e32 v64, 0x5a, v220
	s_nop 0
	v_cndmask_b32_e32 v81, v196, v81, vcc
	v_cmp_gt_u32_e32 vcc, s29, v64
	v_add_u32_e32 v64, 0x79, v220
	s_nop 0
	v_cndmask_b32_e32 v97, v196, v97, vcc
	v_cmp_gt_u32_e32 vcc, s29, v64
	v_add_u32_e32 v64, 0x59, v220
	s_nop 0
	v_cndmask_b32_e32 v82, v196, v82, vcc
	v_cmp_gt_u32_e32 vcc, s29, v64
	v_add_u32_e32 v64, 0x78, v220
	s_nop 0
	v_cndmask_b32_e32 v98, v196, v98, vcc
	v_cmp_gt_u32_e32 vcc, s29, v64
	v_add_u32_e32 v64, 0x58, v220
	s_nop 0
	v_cndmask_b32_e32 v83, v196, v83, vcc
	v_cmp_gt_u32_e32 vcc, s29, v64
	v_add_u32_e32 v64, 0x73, v220
	s_nop 0
	v_cndmask_b32_e32 v99, v196, v99, vcc
	v_cmp_gt_u32_e32 vcc, s29, v64
	v_add_u32_e32 v64, 0x53, v220
	s_nop 0
	v_cndmask_b32_e32 v84, v196, v84, vcc
	v_cmp_gt_u32_e32 vcc, s29, v64
	v_add_u32_e32 v64, 0x72, v220
	s_nop 0
	v_cndmask_b32_e32 v100, v196, v100, vcc
	v_cmp_gt_u32_e32 vcc, s29, v64
	v_add_u32_e32 v64, 0x52, v220
	s_nop 0
	v_cndmask_b32_e32 v85, v196, v85, vcc
	v_cmp_gt_u32_e32 vcc, s29, v64
	v_add_u32_e32 v64, 0x71, v220
	s_nop 0
	v_cndmask_b32_e32 v101, v196, v101, vcc
	v_cmp_gt_u32_e32 vcc, s29, v64
	v_add_u32_e32 v64, 0x51, v220
	s_nop 0
	v_cndmask_b32_e32 v86, v196, v86, vcc
	v_cmp_gt_u32_e32 vcc, s29, v64
	v_add_u32_e32 v64, 0x70, v220
	s_nop 0
	v_cndmask_b32_e32 v102, v196, v102, vcc
	v_cmp_gt_u32_e32 vcc, s29, v64
	v_add_u32_e32 v64, 0x50, v220
	s_nop 0
	v_cndmask_b32_e32 v87, v196, v87, vcc
	v_cmp_gt_u32_e32 vcc, s29, v64
	v_add_u32_e32 v64, 0x6b, v220
	s_nop 0
	v_cndmask_b32_e32 v103, v196, v103, vcc
	v_cmp_gt_u32_e32 vcc, s29, v64
	v_add_u32_e32 v64, 0x4b, v220
	s_nop 0
	v_cndmask_b32_e32 v88, v196, v88, vcc
	v_cmp_gt_u32_e32 vcc, s29, v64
	v_add_u32_e32 v64, 0x6a, v220
	s_nop 0
	v_cndmask_b32_e32 v104, v196, v104, vcc
	v_cmp_gt_u32_e32 vcc, s29, v64
	v_add_u32_e32 v64, 0x4a, v220
	s_nop 0
	v_cndmask_b32_e32 v89, v196, v89, vcc
	v_cmp_gt_u32_e32 vcc, s29, v64
	v_add_u32_e32 v64, 0x69, v220
	s_nop 0
	v_cndmask_b32_e32 v105, v196, v105, vcc
	v_cmp_gt_u32_e32 vcc, s29, v64
	v_add_u32_e32 v64, 0x49, v220
	s_nop 0
	v_cndmask_b32_e32 v90, v196, v90, vcc
	v_cmp_gt_u32_e32 vcc, s29, v64
	v_add_u32_e32 v64, 0x68, v220
	s_nop 0
	v_cndmask_b32_e32 v106, v196, v106, vcc
	v_cmp_gt_u32_e32 vcc, s29, v64
	v_add_u32_e32 v64, 0x48, v220
	s_nop 0
	v_cndmask_b32_e32 v91, v196, v91, vcc
	v_cmp_gt_u32_e32 vcc, s29, v64
	v_add_u32_e32 v64, 0x63, v220
	s_nop 0
	v_cndmask_b32_e32 v107, v196, v107, vcc
	v_cmp_gt_u32_e32 vcc, s29, v64
	v_add_u32_e32 v64, 0x43, v220
	s_nop 0
	v_cndmask_b32_e32 v92, v196, v92, vcc
	v_cmp_gt_u32_e32 vcc, s29, v64
	v_add_u32_e32 v64, 0x62, v220
	s_nop 0
	v_cndmask_b32_e32 v108, v196, v108, vcc
	v_cmp_gt_u32_e32 vcc, s29, v64
	v_add_u32_e32 v64, 0x42, v220
	s_nop 0
	v_cndmask_b32_e32 v93, v196, v93, vcc
	v_cmp_gt_u32_e32 vcc, s29, v64
	v_add_u32_e32 v64, 0x61, v220
	s_nop 0
	v_cndmask_b32_e32 v109, v196, v109, vcc
	v_cmp_gt_u32_e32 vcc, s29, v64
	v_add_u32_e32 v64, 0x41, v220
	s_nop 0
	v_cndmask_b32_e32 v94, v196, v94, vcc
	v_cmp_gt_u32_e32 vcc, s29, v64
	v_add_u32_e32 v64, 0x60, v220
	s_nop 0
	v_cndmask_b32_e32 v110, v196, v110, vcc
	v_cmp_gt_u32_e32 vcc, s29, v64
	v_add_u32_e32 v64, 64, v220
	s_nop 0
	v_cndmask_b32_e32 v95, v196, v95, vcc
	v_cmp_gt_u32_e32 vcc, s29, v64
	s_nop 1
	v_cndmask_b32_e32 v111, v196, v111, vcc

.LBB0_928:
	ds_read2_b64 v[64:67], v185 offset0:64 offset1:96
	v_mov_b64_e32 v[70:71], s[10:11]
	v_mov_b64_e32 v[74:75], s[10:11]
	v_mov_b64_e32 v[68:69], s[8:9]
	v_mov_b64_e32 v[72:73], s[8:9]
	s_waitcnt lgkmcnt(0)
	v_or_b32_e32 v69, 1.0, v65
	v_mov_b32_e32 v68, v64
	v_or_b32_e32 v73, 1.0, v67
	v_mov_b32_e32 v72, v66
	v_cndmask_b32_e64 v129, 0, v218, s[6:7]
	v_cndmask_b32_e64 v130, 0, v219, s[6:7]
	s_add_i32 s3, s74, 1
	s_nop 0
	v_mfma_f32_32x32x16_bf16 v[112:127], v[68:71], v[128:131], 0
	v_mfma_f32_32x32x16_bf16 v[64:79], v[72:75], v[128:131], 0
	ds_read_b128 v[224:227], v212 offset:32768
	ds_read_b128 v[228:231], v212 offset:40960
	ds_read_b128 v[232:235], v211 offset:32768
	ds_read_b128 v[236:239], v211 offset:40960
	s_waitcnt lgkmcnt(3)
	v_mfma_f32_32x32x16_bf16 v[112:127], v[224:227], v[160:163], v[112:127]
	ds_read_b128 v[224:227], v210 offset:32768
	s_waitcnt lgkmcnt(3)
	v_mfma_f32_32x32x16_bf16 v[64:79], v[228:231], v[160:163], v[64:79]
	ds_read_b128 v[228:231], v210 offset:40960
	s_waitcnt lgkmcnt(3)
	v_mfma_f32_32x32x16_bf16 v[112:127], v[232:235], v[156:159], v[112:127]
	ds_read_b128 v[232:235], v209 offset:32768
	s_waitcnt lgkmcnt(3)
	v_mfma_f32_32x32x16_bf16 v[64:79], v[236:239], v[156:159], v[64:79]
	ds_read_b128 v[236:239], v209 offset:40960
	s_waitcnt lgkmcnt(3)
	v_mfma_f32_32x32x16_bf16 v[112:127], v[224:227], v[152:155], v[112:127]
	ds_read_b128 v[224:227], v212 offset:32896
	s_waitcnt lgkmcnt(3)
	v_mfma_f32_32x32x16_bf16 v[64:79], v[228:231], v[152:155], v[64:79]
	ds_read_b128 v[228:231], v212 offset:41088
	s_waitcnt lgkmcnt(3)
	v_mfma_f32_32x32x16_bf16 v[112:127], v[232:235], v[148:151], v[112:127]
	ds_read_b128 v[232:235], v211 offset:32896
	s_waitcnt lgkmcnt(3)
	v_mfma_f32_32x32x16_bf16 v[64:79], v[236:239], v[148:151], v[64:79]
	ds_read_b128 v[236:239], v211 offset:41088
	s_waitcnt lgkmcnt(3)
	v_mfma_f32_32x32x16_bf16 v[112:127], v[224:227], v[144:147], v[112:127]
	ds_read_b128 v[224:227], v210 offset:32896
	s_waitcnt lgkmcnt(3)
	v_mfma_f32_32x32x16_bf16 v[64:79], v[228:231], v[144:147], v[64:79]
	ds_read_b128 v[228:231], v210 offset:41088
	s_waitcnt lgkmcnt(3)
	v_mfma_f32_32x32x16_bf16 v[112:127], v[232:235], v[136:139], v[112:127]
	ds_read_b128 v[232:235], v209 offset:32896
	s_waitcnt lgkmcnt(3)
	v_mfma_f32_32x32x16_bf16 v[64:79], v[236:239], v[136:139], v[64:79]
	ds_read_b128 v[236:239], v209 offset:41088
	s_waitcnt lgkmcnt(3)
	v_mfma_f32_32x32x16_bf16 v[112:127], v[224:227], v[140:143], v[112:127]
	s_waitcnt lgkmcnt(2)
	v_mfma_f32_32x32x16_bf16 v[64:79], v[228:231], v[140:143], v[64:79]
	s_waitcnt lgkmcnt(1)
	v_mfma_f32_32x32x16_bf16 v[112:127], v[232:235], v[132:135], v[112:127]
	s_waitcnt lgkmcnt(0)
	v_mfma_f32_32x32x16_bf16 v[64:79], v[236:239], v[132:135], v[64:79]
	v_add_f32_e32 v129, 0, v80
	v_add_f32_e32 v129, v81, v129
	v_add_f32_e32 v129, v82, v129
	v_add_f32_e32 v129, v83, v129
	v_add_f32_e32 v129, v84, v129
	v_add_f32_e32 v129, v85, v129
	v_add_f32_e32 v129, v86, v129
	v_add_f32_e32 v129, v87, v129
	v_add_f32_e32 v129, v88, v129
	v_add_f32_e32 v129, v89, v129
	v_add_f32_e32 v129, v90, v129
	v_add_f32_e32 v129, v91, v129
	v_exp_f32_e32 v96, v96
	v_add_f32_e32 v129, v92, v129
	v_exp_f32_e32 v97, v97
	v_add_f32_e32 v129, v93, v129
	v_exp_f32_e32 v98, v98
	v_add_f32_e32 v129, v94, v129
	v_exp_f32_e32 v99, v99
	v_add_f32_e32 v129, v95, v129
	v_exp_f32_e32 v100, v100
	v_add_f32_e32 v129, v96, v129
	v_exp_f32_e32 v101, v101
	v_add_f32_e32 v129, v97, v129
	v_exp_f32_e32 v102, v102
	v_add_f32_e32 v129, v98, v129
	v_exp_f32_e32 v103, v103
	v_add_f32_e32 v129, v99, v129
	v_exp_f32_e32 v104, v104
	v_add_f32_e32 v129, v100, v129
	v_exp_f32_e32 v105, v105
	v_add_f32_e32 v129, v101, v129
	v_exp_f32_e32 v106, v106
	v_add_f32_e32 v129, v102, v129
	v_exp_f32_e32 v107, v107
	v_add_f32_e32 v129, v103, v129
	v_exp_f32_e32 v108, v108
	v_add_f32_e32 v129, v104, v129
	v_exp_f32_e32 v109, v109
	v_add_f32_e32 v129, v105, v129
	v_exp_f32_e32 v110, v110
	v_add_f32_e32 v129, v106, v129
	v_exp_f32_e32 v111, v111
	v_add_f32_e32 v129, v107, v129
	v_add_f32_e32 v129, v108, v129
	v_add_f32_e32 v129, v109, v129
	v_add_f32_e32 v129, v110, v129
	v_add_f32_e32 v129, v111, v129
	v_mov_b32_e32 v130, v129
	s_nop 1
	v_permlane32_swap_b32_e32 v129, v130
	v_cvt_pk_bf16_f32 v224, v80, v81
	v_cvt_pk_bf16_f32 v225, v82, v83
	v_cvt_pk_bf16_f32 v226, v84, v85
	v_cvt_pk_bf16_f32 v227, v86, v87
	v_cvt_pk_bf16_f32 v228, v88, v89
	v_cvt_pk_bf16_f32 v229, v90, v91
	v_cvt_pk_bf16_f32 v230, v92, v93
	v_cvt_pk_bf16_f32 v231, v94, v95
	v_cvt_pk_bf16_f32 v232, v96, v97
	v_cvt_pk_bf16_f32 v233, v98, v99
	v_cvt_pk_bf16_f32 v234, v100, v101
	v_cvt_pk_bf16_f32 v235, v102, v103
	v_cvt_pk_bf16_f32 v236, v104, v105
	v_cvt_pk_bf16_f32 v237, v106, v107
	v_cvt_pk_bf16_f32 v238, v108, v109
	v_cvt_pk_bf16_f32 v239, v110, v111
	s_nop 0
	v_permlane32_swap_b32_e32 v224, v226
	v_permlane32_swap_b32_e32 v225, v227
	v_permlane32_swap_b32_e32 v228, v230
	v_permlane32_swap_b32_e32 v229, v231
	v_permlane32_swap_b32_e32 v232, v234
	v_permlane32_swap_b32_e32 v233, v235
	v_permlane32_swap_b32_e32 v236, v238
	v_permlane32_swap_b32_e32 v237, v239
	ds_read_b64_tr_b16 v[240:241], v203 offset:0x4000
	ds_read_b64_tr_b16 v[242:243], v203 offset:0x4800
	ds_read_b64_tr_b16 v[244:245], v203 offset:0x5000
	ds_read_b64_tr_b16 v[246:247], v203 offset:0x5800
	ds_read_b64_tr_b16 v[248:249], v203 offset:0x6000
	ds_read_b64_tr_b16 v[250:251], v203 offset:0x6800
	ds_read_b64_tr_b16 v[192:193], v203 offset:0x7000
	ds_read_b64_tr_b16 v[194:195], v203 offset:0x7800
	s_waitcnt lgkmcnt(0)
	s_nop 0
	v_mfma_f32_32x32x16_bf16 v[48:63], v[224:227], v[240:243], v[48:63]
	v_mfma_f32_32x32x16_bf16 v[48:63], v[228:231], v[244:247], v[48:63]
	v_mfma_f32_32x32x16_bf16 v[48:63], v[232:235], v[248:251], v[48:63]
	v_mfma_f32_32x32x16_bf16 v[48:63], v[236:239], v[192:195], v[48:63]
	ds_read_b64_tr_b16 v[192:193], v203 offset:0x4200
	ds_read_b64_tr_b16 v[194:195], v203 offset:0x4a00
	ds_read_b64_tr_b16 v[240:241], v203 offset:0x5200
	ds_read_b64_tr_b16 v[242:243], v203 offset:0x5a00
	ds_read_b64_tr_b16 v[244:245], v203 offset:0x6200
	ds_read_b64_tr_b16 v[246:247], v203 offset:0x6a00
	ds_read_b64_tr_b16 v[248:249], v203 offset:0x7200
	ds_read_b64_tr_b16 v[250:251], v203 offset:0x7a00
	s_waitcnt lgkmcnt(0)
	s_nop 0
	v_mfma_f32_32x32x16_bf16 v[32:47], v[224:227], v[192:195], v[32:47]
	ds_read_b64_tr_b16 v[192:193], v203 offset:0x4400
	ds_read_b64_tr_b16 v[194:195], v203 offset:0x4c00
	v_mfma_f32_32x32x16_bf16 v[32:47], v[228:231], v[240:243], v[32:47]
	ds_read_b64_tr_b16 v[240:241], v203 offset:0x5400
	ds_read_b64_tr_b16 v[242:243], v203 offset:0x5c00
	v_mfma_f32_32x32x16_bf16 v[32:47], v[232:235], v[244:247], v[32:47]
	ds_read_b64_tr_b16 v[244:245], v203 offset:0x6400
	ds_read_b64_tr_b16 v[246:247], v203 offset:0x6c00
	v_mfma_f32_32x32x16_bf16 v[32:47], v[236:239], v[248:251], v[32:47]
	ds_read_b64_tr_b16 v[248:249], v203 offset:0x7400
	ds_read_b64_tr_b16 v[250:251], v203 offset:0x7c00
	s_waitcnt lgkmcnt(0)
	v_mfma_f32_32x32x16_bf16 v[16:31], v[224:227], v[192:195], v[16:31]
	ds_read_b64_tr_b16 v[192:193], v203 offset:0x4600
	ds_read_b64_tr_b16 v[194:195], v203 offset:0x4e00
	v_mfma_f32_32x32x16_bf16 v[16:31], v[228:231], v[240:243], v[16:31]
	ds_read_b64_tr_b16 v[240:241], v203 offset:0x5600
	ds_read_b64_tr_b16 v[242:243], v203 offset:0x5e00
	v_mfma_f32_32x32x16_bf16 v[16:31], v[232:235], v[244:247], v[16:31]
	ds_read_b64_tr_b16 v[244:245], v203 offset:0x6600
	ds_read_b64_tr_b16 v[246:247], v203 offset:0x6e00
	v_mfma_f32_32x32x16_bf16 v[16:31], v[236:239], v[248:251], v[16:31]
	ds_read_b64_tr_b16 v[248:249], v203 offset:0x7600
	ds_read_b64_tr_b16 v[250:251], v203 offset:0x7e00
	s_waitcnt lgkmcnt(0)
	v_mfma_f32_32x32x16_bf16 v[0:15], v[224:227], v[192:195], v[0:15]
	v_mfma_f32_32x32x16_bf16 v[0:15], v[228:231], v[240:243], v[0:15]
	v_mfma_f32_32x32x16_bf16 v[0:15], v[232:235], v[244:247], v[0:15]
	v_mfma_f32_32x32x16_bf16 v[0:15], v[236:239], v[248:251], v[0:15]
	s_add_i32 s4, s74, 64
	s_cmp_le_i32 s4, s42
	s_cselect_b64 s[4:5], -1, 0
	s_cmp_gt_i32 s3, s16
	s_cselect_b64 s[36:37], -1, 0
	s_and_b64 s[4:5], s[4:5], s[36:37]
	s_and_b64 vcc, exec, s[4:5]
	s_cbranch_vccnz .LBB0_930
	v_add_u32_e32 v192, 59, v220
	v_cmp_gt_u32_e32 vcc, s29, v192
	v_add_u32_e32 v192, 27, v220
	s_nop 0
	v_cndmask_b32_e32 v112, v196, v112, vcc
	v_cmp_gt_u32_e32 vcc, s29, v192
	v_add_u32_e32 v192, 58, v220
	s_nop 0
	v_cndmask_b32_e32 v64, v196, v64, vcc
	v_cmp_gt_u32_e32 vcc, s29, v192
	v_add_u32_e32 v192, 26, v220
	s_nop 0
	v_cndmask_b32_e32 v113, v196, v113, vcc
	v_cmp_gt_u32_e32 vcc, s29, v192
	v_add_u32_e32 v192, 57, v220
	s_nop 0
	v_cndmask_b32_e32 v65, v196, v65, vcc
	v_cmp_gt_u32_e32 vcc, s29, v192
	v_add_u32_e32 v192, 25, v220
	s_nop 0
	v_cndmask_b32_e32 v114, v196, v114, vcc
	v_cmp_gt_u32_e32 vcc, s29, v192
	v_add_u32_e32 v192, 56, v220
	s_nop 0
	v_cndmask_b32_e32 v66, v196, v66, vcc
	v_cmp_gt_u32_e32 vcc, s29, v192
	v_add_u32_e32 v192, 24, v220
	s_nop 0
	v_cndmask_b32_e32 v115, v196, v115, vcc
	v_cmp_gt_u32_e32 vcc, s29, v192
	v_add_u32_e32 v192, 51, v220
	s_nop 0
	v_cndmask_b32_e32 v67, v196, v67, vcc
	v_cmp_gt_u32_e32 vcc, s29, v192
	v_add_u32_e32 v192, 19, v220
	s_nop 0
	v_cndmask_b32_e32 v116, v196, v116, vcc
	v_cmp_gt_u32_e32 vcc, s29, v192
	v_add_u32_e32 v192, 50, v220
	s_nop 0
	v_cndmask_b32_e32 v68, v196, v68, vcc
	v_cmp_gt_u32_e32 vcc, s29, v192
	v_add_u32_e32 v192, 18, v220
	s_nop 0
	v_cndmask_b32_e32 v117, v196, v117, vcc
	v_cmp_gt_u32_e32 vcc, s29, v192
	v_add_u32_e32 v192, 49, v220
	s_nop 0
	v_cndmask_b32_e32 v69, v196, v69, vcc
	v_cmp_gt_u32_e32 vcc, s29, v192
	v_add_u32_e32 v192, 17, v220
	s_nop 0
	v_cndmask_b32_e32 v118, v196, v118, vcc
	v_cmp_gt_u32_e32 vcc, s29, v192
	v_add_u32_e32 v192, 48, v220
	s_nop 0
	v_cndmask_b32_e32 v70, v196, v70, vcc
	v_cmp_gt_u32_e32 vcc, s29, v192
	v_add_u32_e32 v192, 16, v220
	s_nop 0
	v_cndmask_b32_e32 v119, v196, v119, vcc
	v_cmp_gt_u32_e32 vcc, s29, v192
	v_add_u32_e32 v192, 43, v220
	s_nop 0
	v_cndmask_b32_e32 v71, v196, v71, vcc
	v_cmp_gt_u32_e32 vcc, s29, v192
	v_add_u32_e32 v192, 11, v220
	s_nop 0
	v_cndmask_b32_e32 v120, v196, v120, vcc
	v_cmp_gt_u32_e32 vcc, s29, v192
	v_add_u32_e32 v192, 42, v220
	s_nop 0
	v_cndmask_b32_e32 v72, v196, v72, vcc
	v_cmp_gt_u32_e32 vcc, s29, v192
	v_add_u32_e32 v192, 10, v220
	s_nop 0
	v_cndmask_b32_e32 v121, v196, v121, vcc
	v_cmp_gt_u32_e32 vcc, s29, v192
	v_add_u32_e32 v192, 41, v220
	s_nop 0
	v_cndmask_b32_e32 v73, v196, v73, vcc
	v_cmp_gt_u32_e32 vcc, s29, v192
	v_add_u32_e32 v192, 9, v220
	s_nop 0
	v_cndmask_b32_e32 v122, v196, v122, vcc
	v_cmp_gt_u32_e32 vcc, s29, v192
	v_add_u32_e32 v192, 40, v220
	s_nop 0
	v_cndmask_b32_e32 v74, v196, v74, vcc
	v_cmp_gt_u32_e32 vcc, s29, v192
	v_add_u32_e32 v192, 8, v220
	s_nop 0
	v_cndmask_b32_e32 v123, v196, v123, vcc
	v_cmp_gt_u32_e32 vcc, s29, v192
	v_add_u32_e32 v192, 35, v220
	s_nop 0
	v_cndmask_b32_e32 v75, v196, v75, vcc
	v_cmp_gt_u32_e32 vcc, s29, v192
	v_add_u32_e32 v192, 3, v220
	s_nop 0
	v_cndmask_b32_e32 v124, v196, v124, vcc
	v_cmp_gt_u32_e32 vcc, s29, v192
	v_add_u32_e32 v192, 34, v220
	s_nop 0
	v_cndmask_b32_e32 v76, v196, v76, vcc
	v_cmp_gt_u32_e32 vcc, s29, v192
	v_add_u32_e32 v192, 2, v220
	s_nop 0
	v_cndmask_b32_e32 v125, v196, v125, vcc
	v_cmp_gt_u32_e32 vcc, s29, v192
	v_add_u32_e32 v192, 33, v220
	s_nop 0
	v_cndmask_b32_e32 v77, v196, v77, vcc
	v_cmp_gt_u32_e32 vcc, s29, v192
	v_add_u32_e32 v192, 1, v220
	s_nop 0
	v_cndmask_b32_e32 v126, v196, v126, vcc
	v_cmp_gt_u32_e32 vcc, s29, v192
	v_add_u32_e32 v192, 32, v220
	s_nop 0
	v_cndmask_b32_e32 v78, v196, v78, vcc
	v_cmp_gt_u32_e32 vcc, s29, v192
	s_nop 1
	v_cndmask_b32_e32 v127, v196, v127, vcc
	v_cmp_gt_u32_e32 vcc, s29, v220
	s_nop 1
	v_cndmask_b32_e32 v79, v196, v79, vcc

.LBB0_939:
	s_bitcmp0_b32 s43, 0
	s_cselect_b64 s[4:5], -1, 0
	s_and_b64 vcc, exec, s[4:5]
	s_cbranch_vccz .LBB0_941
	v_lshl_add_u32 v86, s43, 9, v213
	v_add_u32_e32 v80, 0xfffffe00, v86
	ds_read_b64 v[84:85], v80
	v_mov_b64_e32 v[82:83], s[10:11]
	v_mov_b64_e32 v[80:81], s[8:9]
	v_add_u32_e32 v80, 0xffffff00, v86
	ds_read_b64 v[100:101], v80
	v_mov_b64_e32 v[98:99], s[10:11]
	v_mov_b64_e32 v[96:97], s[8:9]
	s_waitcnt lgkmcnt(0)
	v_or_b32_e32 v81, 1.0, v85
	v_mov_b32_e32 v80, v84
	v_or_b32_e32 v97, 1.0, v101
	v_mov_b32_e32 v96, v100
	v_cndmask_b32_e64 v129, 0, v218, s[6:7]
	v_cndmask_b32_e64 v130, 0, v219, s[6:7]
	s_nop 1
	v_mfma_f32_32x32x16_bf16 v[80:95], v[80:83], v[128:131], 0
	v_mfma_f32_32x32x16_bf16 v[96:111], v[96:99], v[128:131], 0
	s_waitcnt vmcnt(0)
	ds_read_b128 v[112:115], v212 offset:49152
	ds_read_b128 v[116:119], v212 offset:57344
	ds_read_b128 v[120:123], v211 offset:49152
	ds_read_b128 v[124:127], v211 offset:57344
	s_waitcnt lgkmcnt(3)
	v_mfma_f32_32x32x16_bf16 v[80:95], v[112:115], v[160:163], v[80:95]
	ds_read_b128 v[112:115], v210 offset:49152
	s_waitcnt lgkmcnt(3)
	v_mfma_f32_32x32x16_bf16 v[96:111], v[116:119], v[160:163], v[96:111]
	ds_read_b128 v[116:119], v210 offset:57344
	s_waitcnt lgkmcnt(3)
	v_mfma_f32_32x32x16_bf16 v[80:95], v[120:123], v[156:159], v[80:95]
	ds_read_b128 v[120:123], v209 offset:49152
	s_waitcnt lgkmcnt(3)
	v_mfma_f32_32x32x16_bf16 v[96:111], v[124:127], v[156:159], v[96:111]
	ds_read_b128 v[124:127], v209 offset:57344
	s_waitcnt lgkmcnt(3)
	v_mfma_f32_32x32x16_bf16 v[80:95], v[112:115], v[152:155], v[80:95]
	ds_read_b128 v[112:115], v212 offset:49280
	s_waitcnt lgkmcnt(3)
	v_mfma_f32_32x32x16_bf16 v[96:111], v[116:119], v[152:155], v[96:111]
	ds_read_b128 v[116:119], v212 offset:57472
	s_waitcnt lgkmcnt(3)
	v_mfma_f32_32x32x16_bf16 v[80:95], v[120:123], v[148:151], v[80:95]
	ds_read_b128 v[120:123], v211 offset:49280
	s_waitcnt lgkmcnt(3)
	v_mfma_f32_32x32x16_bf16 v[96:111], v[124:127], v[148:151], v[96:111]
	ds_read_b128 v[124:127], v211 offset:57472
	s_waitcnt lgkmcnt(3)
	v_mfma_f32_32x32x16_bf16 v[80:95], v[112:115], v[144:147], v[80:95]
	ds_read_b128 v[112:115], v210 offset:49280
	s_waitcnt lgkmcnt(3)
	v_mfma_f32_32x32x16_bf16 v[96:111], v[116:119], v[144:147], v[96:111]
	ds_read_b128 v[116:119], v210 offset:57472
	s_waitcnt lgkmcnt(3)
	v_mfma_f32_32x32x16_bf16 v[80:95], v[120:123], v[136:139], v[80:95]
	ds_read_b128 v[120:123], v209 offset:49280
	s_waitcnt lgkmcnt(3)
	v_mfma_f32_32x32x16_bf16 v[96:111], v[124:127], v[136:139], v[96:111]
	ds_read_b128 v[124:127], v209 offset:57472
	s_waitcnt lgkmcnt(3)
	v_mfma_f32_32x32x16_bf16 v[80:95], v[112:115], v[140:143], v[80:95]
	s_waitcnt lgkmcnt(2)
	v_mfma_f32_32x32x16_bf16 v[96:111], v[116:119], v[140:143], v[96:111]
	s_waitcnt lgkmcnt(1)
	v_mfma_f32_32x32x16_bf16 v[80:95], v[120:123], v[132:135], v[80:95]
	s_waitcnt lgkmcnt(0)
	v_mfma_f32_32x32x16_bf16 v[96:111], v[124:127], v[132:135], v[96:111]
.LBB0_941:
	s_add_i32 s0, s81, s0
	s_add_i32 s3, s0, 1
	s_andn2_b32 s3, s3, 63
	s_cmp_gt_i32 s0, -1
	s_cselect_b32 s0, s3, 0
	s_waitcnt vmcnt(0)
	v_add_u32_e32 v112, s0, v205
	v_add_u32_e32 v114, s0, v206
	v_ashrrev_i32_e32 v113, 31, v112
	v_ashrrev_i32_e32 v115, 31, v114
	v_lshlrev_b64 v[120:121], 8, v[112:113]
	v_lshlrev_b64 v[122:123], 8, v[114:115]
	v_lshl_add_u64 v[112:113], s[76:77], 0, v[120:121]
	v_mov_b32_e32 v185, v131
	v_lshl_add_u64 v[114:115], s[76:77], 0, v[122:123]
	v_lshl_add_u64 v[120:121], s[96:97], 0, v[120:121]
	v_lshl_add_u64 v[122:123], s[96:97], 0, v[122:123]
	v_lshl_add_u64 v[112:113], v[112:113], 0, v[184:185]
	v_lshl_add_u64 v[116:117], v[114:115], 0, v[184:185]
	v_lshl_add_u64 v[120:121], v[120:121], 0, v[184:185]
	v_lshl_add_u64 v[124:125], v[122:123], 0, v[184:185]
	global_load_dwordx4 v[112:115], v[112:113], off
	s_nop 0
	global_load_dwordx4 v[116:119], v[116:117], off
	s_nop 0
	global_load_dwordx4 v[120:123], v[120:121], off
	s_nop 0
	global_load_dwordx4 v[124:127], v[124:125], off
	v_or_b32_e32 v130, s58, v197
	v_lshlrev_b64 v[128:129], 8, v[130:131]
	v_lshlrev_b32_e32 v132, 3, v208
	v_ashrrev_i32_e32 v133, 31, v132
	v_lshl_add_u64 v[128:129], s[94:95], 0, v[128:129]
	v_lshl_add_u64 v[128:129], v[132:133], 1, v[128:129]
	global_load_dwordx4 v[160:163], v[128:129], off
	global_load_dwordx4 v[156:159], v[128:129], off offset:32
	global_load_dwordx4 v[152:155], v[128:129], off offset:64
	global_load_dwordx4 v[148:151], v[128:129], off offset:96
	global_load_dwordx4 v[144:147], v[128:129], off offset:128
	global_load_dwordx4 v[136:139], v[128:129], off offset:160
	global_load_dwordx4 v[140:143], v[128:129], off offset:192
	global_load_dwordx4 v[132:135], v[128:129], off offset:224
	v_exp_f32_e32 v128, v64
	v_add_f32_e32 v64, 0, v237
	v_add_f32_e32 v64, v239, v64
	v_add_f32_e32 v64, v235, v64
	v_add_f32_e32 v64, v238, v64
	v_add_f32_e32 v64, v233, v64
	v_add_f32_e32 v64, v236, v64
	v_add_f32_e32 v64, v232, v64
	v_add_f32_e32 v64, v234, v64
	v_add_f32_e32 v64, v229, v64
	v_add_f32_e32 v64, v231, v64
	v_add_f32_e32 v64, v227, v64
	v_add_f32_e32 v64, v230, v64
	v_add_f32_e32 v64, v225, v64
	v_exp_f32_e32 v65, v65
	v_add_f32_e32 v64, v228, v64
	v_exp_f32_e32 v129, v66
	v_add_f32_e32 v64, v224, v64
	v_exp_f32_e32 v130, v67
	v_add_f32_e32 v64, v226, v64
	v_exp_f32_e32 v164, v68
	v_add_f32_e32 v64, v128, v64
	v_exp_f32_e32 v165, v69
	v_add_f32_e32 v64, v65, v64
	v_exp_f32_e32 v166, v70
	v_add_f32_e32 v64, v129, v64
	v_exp_f32_e32 v167, v71
	v_add_f32_e32 v64, v130, v64
	v_exp_f32_e32 v168, v72
	v_add_f32_e32 v64, v164, v64
	v_exp_f32_e32 v169, v73
	v_add_f32_e32 v64, v165, v64
	v_exp_f32_e32 v170, v74
	v_add_f32_e32 v64, v166, v64
	v_exp_f32_e32 v171, v75
	v_add_f32_e32 v64, v167, v64
	v_exp_f32_e32 v172, v76
	v_add_f32_e32 v64, v168, v64
	v_exp_f32_e32 v173, v77
	v_add_f32_e32 v64, v169, v64
	v_exp_f32_e32 v78, v78
	v_add_f32_e32 v64, v170, v64
	v_exp_f32_e32 v79, v79
	v_add_f32_e32 v64, v171, v64
	v_add_f32_e32 v64, v172, v64
	v_add_f32_e32 v64, v173, v64
	v_add_f32_e32 v64, v78, v64
	v_add_f32_e32 v64, v79, v64
	v_mov_b32_e32 v66, v64
	s_nop 1
	v_permlane32_swap_b32_e32 v64, v66
	v_add_f32_e32 v64, v64, v66
	v_fmac_f32_e32 v64, v217, v216
	v_cvt_pk_bf16_f32 v66, v237, v239
	v_cvt_pk_bf16_f32 v67, v235, v238
	v_cvt_pk_bf16_f32 v68, v233, v236
	v_cvt_pk_bf16_f32 v69, v232, v234
	v_cvt_pk_bf16_f32 v70, v229, v231
	v_cvt_pk_bf16_f32 v71, v227, v230
	v_cvt_pk_bf16_f32 v72, v225, v228
	v_cvt_pk_bf16_f32 v73, v224, v226
	v_cvt_pk_bf16_f32 v74, v128, v65
	v_cvt_pk_bf16_f32 v75, v129, v130
	v_cvt_pk_bf16_f32 v76, v164, v165
	v_cvt_pk_bf16_f32 v77, v166, v167
	v_cvt_pk_bf16_f32 v164, v168, v169
	v_cvt_pk_bf16_f32 v165, v170, v171
	v_cvt_pk_bf16_f32 v166, v172, v173
	v_cvt_pk_bf16_f32 v167, v78, v79
	s_nop 0
	v_permlane32_swap_b32_e32 v66, v68
	v_permlane32_swap_b32_e32 v67, v69
	v_permlane32_swap_b32_e32 v70, v72
	v_permlane32_swap_b32_e32 v71, v73
	v_permlane32_swap_b32_e32 v74, v76
	v_permlane32_swap_b32_e32 v75, v77
	v_permlane32_swap_b32_e32 v164, v166
	v_permlane32_swap_b32_e32 v165, v167
	ds_read_b64_tr_b16 v[168:169], v203 offset:0
	ds_read_b64_tr_b16 v[170:171], v203 offset:0x800
	ds_read_b64_tr_b16 v[172:173], v203 offset:0x1000
	ds_read_b64_tr_b16 v[174:175], v203 offset:0x1800
	ds_read_b64_tr_b16 v[176:177], v203 offset:0x2000
	ds_read_b64_tr_b16 v[178:179], v203 offset:0x2800
	ds_read_b64_tr_b16 v[184:185], v203 offset:0x3000
	ds_read_b64_tr_b16 v[186:187], v203 offset:0x3800
	s_waitcnt lgkmcnt(0)
	s_nop 0
	v_mfma_f32_32x32x16_bf16 v[48:63], v[66:69], v[168:171], v[48:63]
	ds_read_b64_tr_b16 v[168:169], v203 offset:0x200
	ds_read_b64_tr_b16 v[170:171], v203 offset:0xa00
	v_mfma_f32_32x32x16_bf16 v[48:63], v[70:73], v[172:175], v[48:63]
	ds_read_b64_tr_b16 v[172:173], v203 offset:0x1200
	ds_read_b64_tr_b16 v[174:175], v203 offset:0x1a00
	v_mfma_f32_32x32x16_bf16 v[48:63], v[74:77], v[176:179], v[48:63]
	ds_read_b64_tr_b16 v[176:177], v203 offset:0x2200
	ds_read_b64_tr_b16 v[178:179], v203 offset:0x2a00
	v_mfma_f32_32x32x16_bf16 v[48:63], v[164:167], v[184:187], v[48:63]
	ds_read_b64_tr_b16 v[184:185], v203 offset:0x3200
	ds_read_b64_tr_b16 v[186:187], v203 offset:0x3a00
	s_waitcnt lgkmcnt(0)
	v_mfma_f32_32x32x16_bf16 v[32:47], v[66:69], v[168:171], v[32:47]
	ds_read_b64_tr_b16 v[168:169], v203 offset:0x400
	ds_read_b64_tr_b16 v[170:171], v203 offset:0xc00
	v_mfma_f32_32x32x16_bf16 v[32:47], v[70:73], v[172:175], v[32:47]
	ds_read_b64_tr_b16 v[172:173], v203 offset:0x1400
	ds_read_b64_tr_b16 v[174:175], v203 offset:0x1c00
	v_mfma_f32_32x32x16_bf16 v[32:47], v[74:77], v[176:179], v[32:47]
	ds_read_b64_tr_b16 v[176:177], v203 offset:0x2400
	ds_read_b64_tr_b16 v[178:179], v203 offset:0x2c00
	v_mfma_f32_32x32x16_bf16 v[32:47], v[164:167], v[184:187], v[32:47]
	ds_read_b64_tr_b16 v[184:185], v203 offset:0x3400
	ds_read_b64_tr_b16 v[186:187], v203 offset:0x3c00
	s_waitcnt lgkmcnt(0)
	v_mfma_f32_32x32x16_bf16 v[16:31], v[66:69], v[168:171], v[16:31]
	ds_read_b64_tr_b16 v[168:169], v203 offset:0x600
	ds_read_b64_tr_b16 v[170:171], v203 offset:0xe00
	v_mfma_f32_32x32x16_bf16 v[16:31], v[70:73], v[172:175], v[16:31]
	ds_read_b64_tr_b16 v[172:173], v203 offset:0x1600
	ds_read_b64_tr_b16 v[174:175], v203 offset:0x1e00
	v_mfma_f32_32x32x16_bf16 v[16:31], v[74:77], v[176:179], v[16:31]
	ds_read_b64_tr_b16 v[176:177], v203 offset:0x2600
	ds_read_b64_tr_b16 v[178:179], v203 offset:0x2e00
	v_mfma_f32_32x32x16_bf16 v[16:31], v[164:167], v[184:187], v[16:31]
	ds_read_b64_tr_b16 v[184:185], v203 offset:0x3600
	ds_read_b64_tr_b16 v[186:187], v203 offset:0x3e00
	s_waitcnt lgkmcnt(0)
	v_mfma_f32_32x32x16_bf16 v[0:15], v[66:69], v[168:171], v[0:15]
	v_mfma_f32_32x32x16_bf16 v[0:15], v[70:73], v[172:175], v[0:15]
	v_mfma_f32_32x32x16_bf16 v[0:15], v[74:77], v[176:179], v[0:15]
	v_mfma_f32_32x32x16_bf16 v[0:15], v[164:167], v[184:187], v[0:15]
	s_andn2_b64 vcc, exec, s[4:5]
	s_cbranch_vccnz .LBB0_952
	s_lshl_b32 s1, s1, 6
	s_sub_i32 s0, s1, 64
	s_add_i32 s1, s1, -1
	s_cmp_gt_i32 s1, s42
	s_cselect_b64 s[4:5], -1, 0
	s_and_b64 vcc, exec, s[4:5]
	s_cbranch_vccnz .LBB0_944
	s_sub_i32 s1, s42, s29
	s_add_i32 s1, s1, 31
	s_cmp_le_i32 s0, s1
	s_cselect_b64 s[4:5], -1, 0

.LBB0_951:
	v_exp_f32_e32 v79, v80
	v_exp_f32_e32 v81, v81
	v_exp_f32_e32 v77, v82
	v_exp_f32_e32 v80, v83
	v_exp_f32_e32 v75, v84
	v_add_f32_e32 v82, 0, v79
	v_exp_f32_e32 v78, v85
	v_add_f32_e32 v82, v81, v82
	v_exp_f32_e32 v74, v86
	v_add_f32_e32 v82, v77, v82
	v_exp_f32_e32 v76, v87
	v_add_f32_e32 v82, v80, v82
	v_exp_f32_e32 v71, v88
	v_add_f32_e32 v82, v75, v82
	v_exp_f32_e32 v73, v89
	v_add_f32_e32 v82, v78, v82
	v_exp_f32_e32 v69, v90
	v_add_f32_e32 v82, v74, v82
	v_exp_f32_e32 v72, v91
	v_add_f32_e32 v82, v76, v82
	v_exp_f32_e32 v67, v92
	v_add_f32_e32 v82, v71, v82
	v_exp_f32_e32 v70, v93
	v_add_f32_e32 v82, v73, v82
	v_exp_f32_e32 v66, v94
	v_add_f32_e32 v82, v69, v82
	v_exp_f32_e32 v68, v95
	v_add_f32_e32 v82, v72, v82
	v_exp_f32_e32 v86, v96
	v_add_f32_e32 v82, v67, v82
	v_exp_f32_e32 v87, v97
	v_add_f32_e32 v82, v70, v82
	v_exp_f32_e32 v88, v98
	v_add_f32_e32 v82, v66, v82
	v_exp_f32_e32 v89, v99
	v_add_f32_e32 v82, v68, v82
	v_exp_f32_e32 v90, v100
	v_add_f32_e32 v82, v86, v82
	v_exp_f32_e32 v91, v101
	v_add_f32_e32 v82, v87, v82
	v_exp_f32_e32 v92, v102
	v_add_f32_e32 v82, v88, v82
	v_exp_f32_e32 v93, v103
	v_add_f32_e32 v82, v89, v82
	v_exp_f32_e32 v94, v104
	v_add_f32_e32 v82, v90, v82
	v_exp_f32_e32 v95, v105
	v_add_f32_e32 v82, v91, v82
	v_exp_f32_e32 v96, v106
	v_add_f32_e32 v82, v92, v82
	v_exp_f32_e32 v97, v107
	v_add_f32_e32 v82, v93, v82
	v_exp_f32_e32 v98, v108
	v_add_f32_e32 v82, v94, v82
	v_exp_f32_e32 v99, v109
	v_add_f32_e32 v82, v95, v82
	v_exp_f32_e32 v100, v110
	v_add_f32_e32 v82, v96, v82
	v_exp_f32_e32 v101, v111
	v_add_f32_e32 v82, v97, v82
	v_add_f32_e32 v82, v98, v82
	v_add_f32_e32 v82, v99, v82
	v_add_f32_e32 v82, v100, v82
	v_add_f32_e32 v82, v101, v82
	v_mov_b32_e32 v83, v82
	s_nop 1
	v_permlane32_swap_b32_e32 v82, v83
	v_add_f32_e32 v102, v82, v83
	v_fmac_f32_e32 v102, v64, v65
	v_cvt_pk_bf16_f32 v82, v79, v81
	v_cvt_pk_bf16_f32 v83, v77, v80
	v_cvt_pk_bf16_f32 v84, v75, v78
	v_cvt_pk_bf16_f32 v85, v74, v76
	v_cvt_pk_bf16_f32 v74, v71, v73
	v_cvt_pk_bf16_f32 v75, v69, v72
	v_cvt_pk_bf16_f32 v76, v67, v70
	v_cvt_pk_bf16_f32 v77, v66, v68
	v_cvt_pk_bf16_f32 v64, v86, v87
	v_cvt_pk_bf16_f32 v65, v88, v89
	v_cvt_pk_bf16_f32 v66, v90, v91
	v_cvt_pk_bf16_f32 v67, v92, v93
	v_cvt_pk_bf16_f32 v68, v94, v95
	v_cvt_pk_bf16_f32 v69, v96, v97
	v_cvt_pk_bf16_f32 v70, v98, v99
	v_cvt_pk_bf16_f32 v71, v100, v101
	s_nop 0
	v_permlane32_swap_b32_e32 v64, v66
	v_permlane32_swap_b32_e32 v82, v84
	v_permlane32_swap_b32_e32 v83, v85
	v_permlane32_swap_b32_e32 v74, v76
	v_permlane32_swap_b32_e32 v75, v77
	v_permlane32_swap_b32_e32 v65, v67
	v_permlane32_swap_b32_e32 v68, v70
	v_permlane32_swap_b32_e32 v69, v71
	ds_read_b64_tr_b16 v[78:79], v203 offset:0x4000
	ds_read_b64_tr_b16 v[80:81], v203 offset:0x4800
	ds_read_b64_tr_b16 v[86:87], v203 offset:0x5000
	ds_read_b64_tr_b16 v[88:89], v203 offset:0x5800
	ds_read_b64_tr_b16 v[90:91], v203 offset:0x6000
	ds_read_b64_tr_b16 v[92:93], v203 offset:0x6800
	ds_read_b64_tr_b16 v[94:95], v203 offset:0x7000
	ds_read_b64_tr_b16 v[96:97], v203 offset:0x7800
	s_waitcnt lgkmcnt(0)
	s_nop 0
	v_mfma_f32_32x32x16_bf16 v[48:63], v[82:85], v[78:81], v[48:63]
	ds_read_b64_tr_b16 v[78:79], v203 offset:0x4200
	ds_read_b64_tr_b16 v[80:81], v203 offset:0x4a00
	v_mfma_f32_32x32x16_bf16 v[48:63], v[74:77], v[86:89], v[48:63]
	ds_read_b64_tr_b16 v[86:87], v203 offset:0x5200
	ds_read_b64_tr_b16 v[88:89], v203 offset:0x5a00
	v_mfma_f32_32x32x16_bf16 v[48:63], v[64:67], v[90:93], v[48:63]
	ds_read_b64_tr_b16 v[90:91], v203 offset:0x6200
	ds_read_b64_tr_b16 v[92:93], v203 offset:0x6a00
	v_mfma_f32_32x32x16_bf16 v[48:63], v[68:71], v[94:97], v[48:63]
	ds_read_b64_tr_b16 v[94:95], v203 offset:0x7200
	ds_read_b64_tr_b16 v[96:97], v203 offset:0x7a00
	s_waitcnt lgkmcnt(0)
	v_mfma_f32_32x32x16_bf16 v[32:47], v[82:85], v[78:81], v[32:47]
	ds_read_b64_tr_b16 v[78:79], v203 offset:0x4400
	ds_read_b64_tr_b16 v[80:81], v203 offset:0x4c00
	v_mfma_f32_32x32x16_bf16 v[32:47], v[74:77], v[86:89], v[32:47]
	ds_read_b64_tr_b16 v[86:87], v203 offset:0x5400
	ds_read_b64_tr_b16 v[88:89], v203 offset:0x5c00
	v_mfma_f32_32x32x16_bf16 v[32:47], v[64:67], v[90:93], v[32:47]
	ds_read_b64_tr_b16 v[90:91], v203 offset:0x6400
	ds_read_b64_tr_b16 v[92:93], v203 offset:0x6c00
	v_mfma_f32_32x32x16_bf16 v[32:47], v[68:71], v[94:97], v[32:47]
	ds_read_b64_tr_b16 v[94:95], v203 offset:0x7400
	ds_read_b64_tr_b16 v[96:97], v203 offset:0x7c00
	s_waitcnt lgkmcnt(0)
	v_mfma_f32_32x32x16_bf16 v[16:31], v[82:85], v[78:81], v[16:31]
	ds_read_b64_tr_b16 v[78:79], v203 offset:0x4600
	ds_read_b64_tr_b16 v[80:81], v203 offset:0x4e00
	v_mfma_f32_32x32x16_bf16 v[16:31], v[74:77], v[86:89], v[16:31]
	ds_read_b64_tr_b16 v[86:87], v203 offset:0x5600
	ds_read_b64_tr_b16 v[88:89], v203 offset:0x5e00
	v_mfma_f32_32x32x16_bf16 v[16:31], v[64:67], v[90:93], v[16:31]
	ds_read_b64_tr_b16 v[90:91], v203 offset:0x6600
	ds_read_b64_tr_b16 v[92:93], v203 offset:0x6e00
	v_mfma_f32_32x32x16_bf16 v[16:31], v[68:71], v[94:97], v[16:31]
	ds_read_b64_tr_b16 v[94:95], v203 offset:0x7600
	ds_read_b64_tr_b16 v[96:97], v203 offset:0x7e00
	s_waitcnt lgkmcnt(0)
	v_mfma_f32_32x32x16_bf16 v[0:15], v[82:85], v[78:81], v[0:15]
	v_mfma_f32_32x32x16_bf16 v[0:15], v[74:77], v[86:89], v[0:15]
	v_mfma_f32_32x32x16_bf16 v[0:15], v[64:67], v[90:93], v[0:15]
	v_mfma_f32_32x32x16_bf16 v[0:15], v[68:71], v[94:97], v[0:15]
	v_mov_b32_e32 v64, v102

.LBB0_1108:
	s_or_b64 exec, exec, s[4:5]
	v_ashrrev_i32_e32 v166, 4, v49
	v_and_b32_e32 v10, 0xfffff0, v166
	v_lshlrev_b32_e32 v11, 1, v166
	v_and_or_b32 v10, v11, 8, v10
	v_lshrrev_b32_e32 v11, 1, v166
	v_and_b32_e32 v13, 3, v166
	v_add_u32_e32 v168, 32, v166
	v_and_or_b32 v11, v11, 4, v13
	v_and_b32_e32 v13, 0xfffff0, v168
	v_lshlrev_b32_e32 v14, 1, v168
	v_and_or_b32 v13, v14, 8, v13
	v_and_b32_e32 v9, 0x78, v48
	v_lshrrev_b32_e32 v10, 1, v10
	v_bfe_u32 v12, v48, 5, 2
	v_lshrrev_b32_e32 v13, 1, v13
	v_and_b32_e32 v171, 31, v165
	v_ashrrev_i32_e32 v51, 5, v165
	v_readlane_b32 s0, v255, 18
	v_or_b32_e32 v10, v10, v12
	v_lshlrev_b32_e32 v130, 1, v9
	v_or_b32_e32 v12, v13, v12
	v_or_b32_e32 v8, s0, v171
	v_lshlrev_b32_e32 v164, 2, v51
	v_lshlrev_b32_e32 v50, 3, v171
	v_lshlrev_b32_e32 v10, 9, v10
	v_lshlrev_b32_e32 v11, 6, v11
	v_and_b32_e32 v9, 48, v130
	v_lshlrev_b32_e32 v12, 9, v12
	v_sub_u32_e32 v173, v8, v164
	v_add_u32_e32 v8, 0, v50
	v_or3_b32 v10, v10, v11, v9
	v_or3_b32 v9, v12, v11, v9
	s_mov_b32 s71, s11
	v_add_u32_e32 v8, 0x10800, v8
	v_add_u32_e32 v185, 0, v10
	v_add_u32_e32 v186, 0, v9
	s_waitcnt lgkmcnt(0)
	s_barrier
	ds_write_b128 v185, v[0:3]
	ds_write_b128 v186, v[4:7]
	v_ashrrev_i32_e32 v167, 31, v166
	v_lshlrev_b64 v[0:1], 8, v[166:167]
	s_mov_b64 s[4:5], 0x4000
	v_lshl_add_u64 v[2:3], v[0:1], 0, s[4:5]
	s_mov_b64 s[4:5], 0x6000
	v_lshl_add_u64 v[4:5], s[46:47], 0, v[2:3]
	v_lshl_add_u64 v[0:1], v[0:1], 0, s[4:5]
	v_lshl_add_u64 v[2:3], s[72:73], 0, v[2:3]
	v_lshl_add_u64 v[4:5], v[4:5], 0, v[130:131]
	v_lshl_add_u64 v[6:7], s[46:47], 0, v[0:1]
	v_lshl_add_u64 v[2:3], v[2:3], 0, v[130:131]
	v_lshl_add_u64 v[0:1], s[72:73], 0, v[0:1]
	v_lshl_add_u64 v[6:7], v[6:7], 0, v[130:131]
	global_load_dwordx4 v[32:35], v[4:5], off
	global_load_dwordx4 v[36:39], v[6:7], off
	v_lshl_add_u64 v[0:1], v[0:1], 0, v[130:131]
	global_load_dwordx4 v[40:43], v[2:3], off
	global_load_dwordx4 v[44:47], v[0:1], off
	ds_read2_b64 v[0:3], v8 offset1:32
	v_mov_b64_e32 v[4:5], s[8:9]
	v_mov_b64_e32 v[6:7], s[10:11]
	v_cmp_gt_u32_e64 s[6:7], 32, v165
	s_waitcnt lgkmcnt(0)
	v_or_b32_e32 v5, 1.0, v1
	v_mov_b32_e32 v4, v0
	v_cndmask_b32_e64 v128, 0, v204, s[6:7]
	v_cndmask_b32_e64 v129, 0, v191, s[6:7]
	v_mov_b64_e32 v[8:9], v[128:129]
	v_mov_b64_e32 v[10:11], v[130:131]
	v_mov_b32_e32 v10, s11
	v_or_b32_e32 v0, 1.0, v3
	s_nop 0
	v_mfma_f32_32x32x16_bf16 v[16:31], v[4:7], v[8:11], 0
	v_mov_b64_e32 v[4:5], s[8:9]
	v_mov_b64_e32 v[6:7], s[10:11]
	v_mov_b32_e32 v4, v2
	v_mov_b32_e32 v5, v0
	s_nop 1
	v_mfma_f32_32x32x16_bf16 v[0:15], v[4:7], v[8:11], 0
	v_lshlrev_b32_e32 v57, 4, v51
	v_lshlrev_b32_e32 v51, 4, v165
	v_and_b32_e32 v58, 0x70, v51
	v_lshlrev_b32_e32 v56, 8, v171
	v_xad_u32 v52, v58, v57, 0
	v_add_u32_e32 v181, v52, v56
	ds_read_b128 v[52:55], v181 offset:32768
	v_add_u32_e32 v59, 32, v57
	v_xad_u32 v59, v59, v58, 0
	v_add_u32_e32 v180, v59, v56
	v_add_u32_e32 v59, 64, v57
	v_xad_u32 v59, v59, v58, 0
	v_add_u32_e32 v179, v59, v56
	s_waitcnt lgkmcnt(0)
	v_mfma_f32_32x32x16_bf16 v[16:31], v[52:55], v[144:147], v[16:31]
	ds_read_b128 v[52:55], v181 offset:40960
	v_add_u32_e32 v57, 0x60, v57
	v_xad_u32 v57, v57, v58, 0
	v_add_u32_e32 v169, v57, v56
	s_waitcnt lgkmcnt(0)
	v_mfma_f32_32x32x16_bf16 v[0:15], v[52:55], v[144:147], v[0:15]
	ds_read_b128 v[52:55], v180 offset:32768
	s_waitcnt lgkmcnt(0)
	v_mfma_f32_32x32x16_bf16 v[16:31], v[52:55], v[140:143], v[16:31]
	ds_read_b128 v[52:55], v180 offset:40960
	s_waitcnt lgkmcnt(0)
	v_mfma_f32_32x32x16_bf16 v[0:15], v[52:55], v[140:143], v[0:15]
	ds_read_b128 v[52:55], v179 offset:32768
	s_waitcnt lgkmcnt(0)
	v_mfma_f32_32x32x16_bf16 v[16:31], v[52:55], v[136:139], v[16:31]
	ds_read_b128 v[52:55], v179 offset:40960
	s_waitcnt lgkmcnt(0)
	v_mfma_f32_32x32x16_bf16 v[0:15], v[52:55], v[136:139], v[0:15]
	ds_read_b128 v[52:55], v169 offset:32768
	s_waitcnt lgkmcnt(0)
	v_mfma_f32_32x32x16_bf16 v[16:31], v[52:55], v[132:135], v[16:31]
	ds_read_b128 v[52:55], v169 offset:40960
	s_waitcnt lgkmcnt(0)
	v_mfma_f32_32x32x16_bf16 v[0:15], v[52:55], v[132:135], v[0:15]
	ds_read_b128 v[52:55], v181 offset:32896
	s_waitcnt lgkmcnt(0)
	v_mfma_f32_32x32x16_bf16 v[16:31], v[52:55], v[124:127], v[16:31]
	ds_read_b128 v[52:55], v181 offset:41088
	s_waitcnt lgkmcnt(0)
	v_mfma_f32_32x32x16_bf16 v[0:15], v[52:55], v[124:127], v[0:15]
	ds_read_b128 v[52:55], v180 offset:32896
	s_waitcnt lgkmcnt(0)
	v_mfma_f32_32x32x16_bf16 v[16:31], v[52:55], v[120:123], v[16:31]
	ds_read_b128 v[52:55], v180 offset:41088
	s_waitcnt lgkmcnt(0)
	v_mfma_f32_32x32x16_bf16 v[0:15], v[52:55], v[120:123], v[0:15]
	ds_read_b128 v[52:55], v179 offset:32896
	s_waitcnt lgkmcnt(0)
	v_mfma_f32_32x32x16_bf16 v[16:31], v[52:55], v[116:119], v[16:31]
	ds_read_b128 v[52:55], v179 offset:41088
	s_waitcnt lgkmcnt(0)
	v_mfma_f32_32x32x16_bf16 v[0:15], v[52:55], v[116:119], v[0:15]
	ds_read_b128 v[52:55], v169 offset:32896
	s_waitcnt lgkmcnt(0)
	v_mfma_f32_32x32x16_bf16 v[16:31], v[52:55], v[112:115], v[16:31]
	ds_read_b128 v[52:55], v169 offset:41088
	s_waitcnt lgkmcnt(0)
	v_mfma_f32_32x32x16_bf16 v[0:15], v[52:55], v[112:115], v[0:15]
	v_readlane_b32 s4, v255, 19
	v_readlane_b32 s5, v255, 20
	s_andn2_b64 vcc, exec, s[4:5]
	s_cbranch_vccnz .LBB0_1110
	s_mov_b32 s0, 0x100000
	v_cmp_gt_u32_e32 vcc, s0, v173
	v_subrev_u32_e32 v52, 32, v173
	s_nop 0
	v_cndmask_b32_e32 v16, v196, v16, vcc
	v_cmp_gt_u32_e32 vcc, s0, v52
	v_add_u32_e32 v52, -1, v173
	s_nop 0
	v_cndmask_b32_e32 v0, v196, v0, vcc
	v_cmp_gt_u32_e32 vcc, s0, v52
	v_subrev_u32_e32 v52, 33, v173
	s_nop 0
	v_cndmask_b32_e32 v17, v196, v17, vcc
	v_cmp_gt_u32_e32 vcc, s0, v52
	v_add_u32_e32 v52, -2, v173
	s_nop 0
	v_cndmask_b32_e32 v1, v196, v1, vcc
	v_cmp_gt_u32_e32 vcc, s0, v52
	v_subrev_u32_e32 v52, 34, v173
	s_nop 0
	v_cndmask_b32_e32 v18, v196, v18, vcc
	v_cmp_gt_u32_e32 vcc, s0, v52
	v_add_u32_e32 v52, -3, v173
	s_nop 0
	v_cndmask_b32_e32 v2, v196, v2, vcc
	v_cmp_gt_u32_e32 vcc, s0, v52
	v_subrev_u32_e32 v52, 35, v173
	s_nop 0
	v_cndmask_b32_e32 v19, v196, v19, vcc
	v_cmp_gt_u32_e32 vcc, s0, v52
	v_add_u32_e32 v52, -8, v173
	s_nop 0
	v_cndmask_b32_e32 v3, v196, v3, vcc
	v_cmp_gt_u32_e32 vcc, s0, v52
	v_subrev_u32_e32 v52, 40, v173
	s_nop 0
	v_cndmask_b32_e32 v20, v196, v20, vcc
	v_cmp_gt_u32_e32 vcc, s0, v52
	v_add_u32_e32 v52, -9, v173
	s_nop 0
	v_cndmask_b32_e32 v4, v196, v4, vcc
	v_cmp_gt_u32_e32 vcc, s0, v52
	v_subrev_u32_e32 v52, 41, v173
	s_nop 0
	v_cndmask_b32_e32 v21, v196, v21, vcc
	v_cmp_gt_u32_e32 vcc, s0, v52
	v_add_u32_e32 v52, -10, v173
	s_nop 0
	v_cndmask_b32_e32 v5, v196, v5, vcc
	v_cmp_gt_u32_e32 vcc, s0, v52
	v_subrev_u32_e32 v52, 42, v173
	s_nop 0
	v_cndmask_b32_e32 v22, v196, v22, vcc
	v_cmp_gt_u32_e32 vcc, s0, v52
	v_add_u32_e32 v52, -11, v173
	s_nop 0
	v_cndmask_b32_e32 v6, v196, v6, vcc
	v_cmp_gt_u32_e32 vcc, s0, v52
	v_subrev_u32_e32 v52, 43, v173
	s_nop 0
	v_cndmask_b32_e32 v23, v196, v23, vcc
	v_cmp_gt_u32_e32 vcc, s0, v52
	v_add_u32_e32 v52, -16, v173
	s_nop 0
	v_cndmask_b32_e32 v7, v196, v7, vcc
	v_cmp_gt_u32_e32 vcc, s0, v52
	v_subrev_u32_e32 v52, 48, v173
	s_nop 0
	v_cndmask_b32_e32 v24, v196, v24, vcc
	v_cmp_gt_u32_e32 vcc, s0, v52
	v_subrev_u32_e32 v52, 17, v173
	s_nop 0
	v_cndmask_b32_e32 v8, v196, v8, vcc
	v_cmp_gt_u32_e32 vcc, s0, v52
	v_subrev_u32_e32 v52, 49, v173
	s_nop 0
	v_cndmask_b32_e32 v25, v196, v25, vcc
	v_cmp_gt_u32_e32 vcc, s0, v52
	v_subrev_u32_e32 v52, 18, v173
	s_nop 0
	v_cndmask_b32_e32 v9, v196, v9, vcc
	v_cmp_gt_u32_e32 vcc, s0, v52
	v_subrev_u32_e32 v52, 50, v173
	s_nop 0
	v_cndmask_b32_e32 v26, v196, v26, vcc
	v_cmp_gt_u32_e32 vcc, s0, v52
	v_subrev_u32_e32 v52, 19, v173
	s_nop 0
	v_cndmask_b32_e32 v10, v196, v10, vcc
	v_cmp_gt_u32_e32 vcc, s0, v52
	v_subrev_u32_e32 v52, 51, v173
	s_nop 0
	v_cndmask_b32_e32 v27, v196, v27, vcc
	v_cmp_gt_u32_e32 vcc, s0, v52
	v_subrev_u32_e32 v52, 24, v173
	s_nop 0
	v_cndmask_b32_e32 v11, v196, v11, vcc
	v_cmp_gt_u32_e32 vcc, s0, v52
	v_subrev_u32_e32 v52, 56, v173
	s_nop 0
	v_cndmask_b32_e32 v28, v196, v28, vcc
	v_cmp_gt_u32_e32 vcc, s0, v52
	v_subrev_u32_e32 v52, 25, v173
	s_nop 0
	v_cndmask_b32_e32 v12, v196, v12, vcc
	v_cmp_gt_u32_e32 vcc, s0, v52
	v_subrev_u32_e32 v52, 57, v173
	s_nop 0
	v_cndmask_b32_e32 v29, v196, v29, vcc
	v_cmp_gt_u32_e32 vcc, s0, v52
	v_subrev_u32_e32 v52, 26, v173
	s_nop 0
	v_cndmask_b32_e32 v13, v196, v13, vcc
	v_cmp_gt_u32_e32 vcc, s0, v52
	v_subrev_u32_e32 v52, 58, v173
	s_nop 0
	v_cndmask_b32_e32 v30, v196, v30, vcc
	v_cmp_gt_u32_e32 vcc, s0, v52
	v_subrev_u32_e32 v52, 27, v173
	s_nop 0
	v_cndmask_b32_e32 v14, v196, v14, vcc
	v_cmp_gt_u32_e32 vcc, s0, v52
	v_subrev_u32_e32 v52, 59, v173
	s_nop 0
	v_cndmask_b32_e32 v31, v196, v31, vcc
	v_cmp_gt_u32_e32 vcc, s0, v52
	s_nop 1
	v_cndmask_b32_e32 v15, v196, v15, vcc

.LBB0_1112:
	v_lshlrev_b32_e32 v52, 8, v166
	v_and_b32_e32 v49, 0x70, v49
	v_bitop3_b32 v49, v130, v52, v49 bitop3:0xde
	v_and_b32_e32 v51, 0xc0, v51
	v_lshlrev_b32_e32 v52, 1, v165
	v_and_or_b32 v51, v48, 24, v51
	v_and_b32_e32 v52, 32, v52
	v_and_b32_e32 v48, 0x100, v48
	s_cmp_lg_u32 0, -1
	v_or3_b32 v48, v51, v52, v48
	s_cselect_b32 s0, 0, 0
	v_add_u32_e32 v175, s0, v48
	v_exp_f32_e32 v48, v16
	v_exp_f32_e32 v51, v17
	v_exp_f32_e32 v52, v18
	v_exp_f32_e32 v53, v19
	v_exp_f32_e32 v54, v20
	v_exp_f32_e32 v55, v21
	v_exp_f32_e32 v56, v22
	v_exp_f32_e32 v57, v23
	v_exp_f32_e32 v58, v24
	v_exp_f32_e32 v59, v25
	v_exp_f32_e32 v60, v26
	v_exp_f32_e32 v61, v27
	v_exp_f32_e32 v62, v28
	v_exp_f32_e32 v63, v29
	s_waitcnt vmcnt(0)
	v_add_u32_e32 v174, 0, v49
	v_lshl_add_u64 v[148:149], s[46:47], 0, v[130:131]
	v_lshl_add_u64 v[156:157], s[72:73], 0, v[130:131]
	v_exp_f32_e32 v153, v30
	v_exp_f32_e32 v154, v31
	s_waitcnt vmcnt(0)
	ds_write_b128 v185, v[32:35] offset:16384
	ds_write_b128 v186, v[36:39] offset:16384
	ds_write_b128 v174, v[40:43] offset:49152
	ds_write_b128 v174, v[44:47] offset:57344
	s_waitcnt lgkmcnt(0)
	s_barrier
	v_lshlrev_b64 v[16:17], 8, v[166:167]
	v_lshl_add_u64 v[18:19], v[16:17], 0, s[34:35]
	v_lshl_add_u64 v[20:21], v[148:149], 0, v[18:19]
	v_lshl_add_u64 v[16:17], v[16:17], 0, s[54:55]
	v_lshl_add_u64 v[18:19], v[156:157], 0, v[18:19]
	v_lshl_add_u64 v[22:23], v[148:149], 0, v[16:17]
	global_load_dwordx4 v[96:99], v[20:21], off
	global_load_dwordx4 v[100:103], v[22:23], off
	v_lshl_add_u64 v[16:17], v[156:157], 0, v[16:17]
	global_load_dwordx4 v[104:107], v[18:19], off
	global_load_dwordx4 v[108:111], v[16:17], off
	s_add_i32 s0, 0, 0x10800
	v_add_u32_e32 v198, s0, v50
	ds_read2_b64 v[16:19], v198 offset0:64 offset1:96
	v_mov_b64_e32 v[22:23], s[10:11]
	v_mov_b64_e32 v[26:27], s[10:11]
	v_mov_b64_e32 v[20:21], s[8:9]
	v_mov_b64_e32 v[24:25], s[8:9]
	s_waitcnt lgkmcnt(0)
	v_or_b32_e32 v21, 1.0, v17
	v_mov_b32_e32 v20, v16
	v_or_b32_e32 v25, 1.0, v19
	v_mov_b32_e32 v24, v18
	v_mov_b64_e32 v[28:29], v[128:129]
	v_cndmask_b32_e64 v16, 0, v197, s[6:7]
	v_mov_b64_e32 v[30:31], v[130:131]
	v_mov_b32_e32 v30, v16
	s_nop 1
	v_mfma_f32_32x32x16_bf16 v[64:79], v[20:23], v[28:31], 0
	v_mfma_f32_32x32x16_bf16 v[80:95], v[24:27], v[28:31], 0
	ds_read_b128 v[16:19], v181 offset:49152
	ds_read_b128 v[20:23], v181 offset:57344
	ds_read_b128 v[24:27], v180 offset:49152
	ds_read_b128 v[28:31], v180 offset:57344
	s_waitcnt lgkmcnt(3)
	v_mfma_f32_32x32x16_bf16 v[64:79], v[16:19], v[144:147], v[64:79]
	ds_read_b128 v[16:19], v179 offset:49152
	s_waitcnt lgkmcnt(3)
	v_mfma_f32_32x32x16_bf16 v[80:95], v[20:23], v[144:147], v[80:95]
	ds_read_b128 v[20:23], v179 offset:57344
	s_waitcnt lgkmcnt(3)
	v_mfma_f32_32x32x16_bf16 v[64:79], v[24:27], v[140:143], v[64:79]
	ds_read_b128 v[24:27], v169 offset:49152
	s_waitcnt lgkmcnt(3)
	v_mfma_f32_32x32x16_bf16 v[80:95], v[28:31], v[140:143], v[80:95]
	ds_read_b128 v[28:31], v169 offset:57344
	s_waitcnt lgkmcnt(3)
	v_mfma_f32_32x32x16_bf16 v[64:79], v[16:19], v[136:139], v[64:79]
	ds_read_b128 v[16:19], v181 offset:49280
	s_waitcnt lgkmcnt(3)
	v_mfma_f32_32x32x16_bf16 v[80:95], v[20:23], v[136:139], v[80:95]
	ds_read_b128 v[20:23], v181 offset:57472
	s_waitcnt lgkmcnt(3)
	v_mfma_f32_32x32x16_bf16 v[64:79], v[24:27], v[132:135], v[64:79]
	ds_read_b128 v[24:27], v180 offset:49280
	s_waitcnt lgkmcnt(3)
	v_mfma_f32_32x32x16_bf16 v[80:95], v[28:31], v[132:135], v[80:95]
	ds_read_b128 v[28:31], v180 offset:57472
	s_waitcnt lgkmcnt(3)
	v_mfma_f32_32x32x16_bf16 v[64:79], v[16:19], v[124:127], v[64:79]
	ds_read_b128 v[16:19], v179 offset:49280
	s_waitcnt lgkmcnt(3)
	v_mfma_f32_32x32x16_bf16 v[80:95], v[20:23], v[124:127], v[80:95]
	ds_read_b128 v[20:23], v179 offset:57472
	s_waitcnt lgkmcnt(3)
	v_mfma_f32_32x32x16_bf16 v[64:79], v[24:27], v[120:123], v[64:79]
	ds_read_b128 v[24:27], v169 offset:49280
	s_waitcnt lgkmcnt(3)
	v_mfma_f32_32x32x16_bf16 v[80:95], v[28:31], v[120:123], v[80:95]
	ds_read_b128 v[28:31], v169 offset:57472
	s_waitcnt lgkmcnt(3)
	v_mfma_f32_32x32x16_bf16 v[64:79], v[16:19], v[116:119], v[64:79]
	s_waitcnt lgkmcnt(2)
	v_mfma_f32_32x32x16_bf16 v[80:95], v[20:23], v[116:119], v[80:95]
	s_waitcnt lgkmcnt(1)
	v_mfma_f32_32x32x16_bf16 v[64:79], v[24:27], v[112:115], v[64:79]
	s_waitcnt lgkmcnt(0)
	v_mfma_f32_32x32x16_bf16 v[80:95], v[28:31], v[112:115], v[80:95]
	v_add_f32_e32 v16, 0, v48
	v_add_f32_e32 v16, v51, v16
	v_add_f32_e32 v16, v52, v16
	v_add_f32_e32 v16, v53, v16
	v_add_f32_e32 v16, v54, v16
	v_add_f32_e32 v16, v55, v16
	v_add_f32_e32 v16, v56, v16
	v_add_f32_e32 v16, v57, v16
	v_add_f32_e32 v16, v58, v16
	v_add_f32_e32 v16, v59, v16
	v_add_f32_e32 v16, v60, v16
	v_add_f32_e32 v16, v61, v16
	v_exp_f32_e32 v0, v0
	v_add_f32_e32 v16, v62, v16
	v_exp_f32_e32 v1, v1
	v_add_f32_e32 v16, v63, v16
	v_exp_f32_e32 v2, v2
	v_add_f32_e32 v16, v153, v16
	v_exp_f32_e32 v3, v3
	v_add_f32_e32 v16, v154, v16
	v_exp_f32_e32 v4, v4
	v_add_f32_e32 v16, v0, v16
	v_exp_f32_e32 v5, v5
	v_add_f32_e32 v16, v1, v16
	v_exp_f32_e32 v6, v6
	v_add_f32_e32 v16, v2, v16
	v_exp_f32_e32 v7, v7
	v_add_f32_e32 v16, v3, v16
	v_exp_f32_e32 v8, v8
	v_add_f32_e32 v16, v4, v16
	v_exp_f32_e32 v9, v9
	v_add_f32_e32 v16, v5, v16
	v_exp_f32_e32 v10, v10
	v_add_f32_e32 v16, v6, v16
	v_exp_f32_e32 v11, v11
	v_add_f32_e32 v16, v7, v16
	v_exp_f32_e32 v12, v12
	v_add_f32_e32 v16, v8, v16
	v_exp_f32_e32 v13, v13
	v_add_f32_e32 v16, v9, v16
	v_exp_f32_e32 v14, v14
	v_add_f32_e32 v16, v10, v16
	v_exp_f32_e32 v15, v15
	v_add_f32_e32 v16, v11, v16
	v_add_f32_e32 v16, v12, v16
	v_add_f32_e32 v16, v13, v16
	v_add_f32_e32 v16, v14, v16
	v_add_f32_e32 v176, v15, v16
	v_mov_b32_e32 v177, v176
	v_cvt_pk_bf16_f32 v48, v48, v51
	v_cvt_pk_bf16_f32 v49, v52, v53
	v_cvt_pk_bf16_f32 v50, v54, v55
	v_cvt_pk_bf16_f32 v51, v56, v57
	s_nop 1
	v_permlane32_swap_b32_e32 v176, v177
	v_permlane32_swap_b32_e32 v48, v50
	v_permlane32_swap_b32_e32 v49, v51
	v_cvt_pk_bf16_f32 v150, v58, v59
	v_cvt_pk_bf16_f32 v151, v60, v61
	v_cvt_pk_bf16_f32 v152, v62, v63
	v_cvt_pk_bf16_f32 v153, v153, v154
	v_cvt_pk_bf16_f32 v158, v0, v1
	v_cvt_pk_bf16_f32 v159, v2, v3
	v_cvt_pk_bf16_f32 v160, v4, v5
	v_cvt_pk_bf16_f32 v161, v6, v7
	v_cvt_pk_bf16_f32 v192, v8, v9
	v_cvt_pk_bf16_f32 v193, v10, v11
	v_cvt_pk_bf16_f32 v194, v12, v13
	v_cvt_pk_bf16_f32 v195, v14, v15
	s_nop 0
	v_permlane32_swap_b32_e32 v150, v152
	v_permlane32_swap_b32_e32 v151, v153
	v_permlane32_swap_b32_e32 v158, v160
	v_permlane32_swap_b32_e32 v159, v161
	v_permlane32_swap_b32_e32 v192, v194
	v_permlane32_swap_b32_e32 v193, v195
	ds_read_b64_tr_b16 v[0:1], v175 offset:0
	ds_read_b64_tr_b16 v[2:3], v175 offset:0x800
	ds_read_b64_tr_b16 v[16:17], v175 offset:0x1000
	ds_read_b64_tr_b16 v[18:19], v175 offset:0x1800
	ds_read_b64_tr_b16 v[20:21], v175 offset:0x2000
	ds_read_b64_tr_b16 v[22:23], v175 offset:0x2800
	ds_read_b64_tr_b16 v[24:25], v175 offset:0x3000
	ds_read_b64_tr_b16 v[26:27], v175 offset:0x3800
	s_waitcnt lgkmcnt(0)
	s_nop 0
	v_mfma_f32_32x32x16_bf16 v[0:15], v[48:51], v[0:3], 0
	v_mfma_f32_32x32x16_bf16 v[0:15], v[150:153], v[16:19], v[0:15]
	ds_read_b64_tr_b16 v[16:17], v175 offset:0x200
	ds_read_b64_tr_b16 v[18:19], v175 offset:0xa00
	ds_read_b64_tr_b16 v[32:33], v175 offset:0x1200
	ds_read_b64_tr_b16 v[34:35], v175 offset:0x1a00
	ds_read_b64_tr_b16 v[36:37], v175 offset:0x2200
	ds_read_b64_tr_b16 v[38:39], v175 offset:0x2a00
	ds_read_b64_tr_b16 v[40:41], v175 offset:0x3200
	v_mfma_f32_32x32x16_bf16 v[0:15], v[158:161], v[20:23], v[0:15]
	ds_read_b64_tr_b16 v[42:43], v175 offset:0x3a00
	s_waitcnt lgkmcnt(0)
	v_mfma_f32_32x32x16_bf16 v[0:15], v[192:195], v[24:27], v[0:15]
	v_mfma_f32_32x32x16_bf16 v[16:31], v[48:51], v[16:19], 0
	v_mfma_f32_32x32x16_bf16 v[16:31], v[150:153], v[32:35], v[16:31]
	ds_read_b64_tr_b16 v[32:33], v175 offset:0x400
	ds_read_b64_tr_b16 v[34:35], v175 offset:0xc00
	ds_read_b64_tr_b16 v[52:53], v175 offset:0x1400
	ds_read_b64_tr_b16 v[54:55], v175 offset:0x1c00
	ds_read_b64_tr_b16 v[56:57], v175 offset:0x2400
	ds_read_b64_tr_b16 v[58:59], v175 offset:0x2c00
	ds_read_b64_tr_b16 v[60:61], v175 offset:0x3400
	v_mfma_f32_32x32x16_bf16 v[16:31], v[158:161], v[36:39], v[16:31]
	ds_read_b64_tr_b16 v[62:63], v175 offset:0x3c00
	s_waitcnt lgkmcnt(0)
	v_mfma_f32_32x32x16_bf16 v[16:31], v[192:195], v[40:43], v[16:31]
	v_mfma_f32_32x32x16_bf16 v[32:47], v[48:51], v[32:35], 0
	v_mfma_f32_32x32x16_bf16 v[32:47], v[150:153], v[52:55], v[32:47]
	ds_read_b64_tr_b16 v[52:53], v175 offset:0x600
	ds_read_b64_tr_b16 v[54:55], v175 offset:0xe00
	ds_read_b64_tr_b16 v[200:201], v175 offset:0x1600
	ds_read_b64_tr_b16 v[202:203], v175 offset:0x1e00
	ds_read_b64_tr_b16 v[206:207], v175 offset:0x2600
	ds_read_b64_tr_b16 v[208:209], v175 offset:0x2e00
	ds_read_b64_tr_b16 v[210:211], v175 offset:0x3600
	v_mfma_f32_32x32x16_bf16 v[32:47], v[158:161], v[56:59], v[32:47]
	ds_read_b64_tr_b16 v[212:213], v175 offset:0x3e00
	s_waitcnt lgkmcnt(0)
	v_mfma_f32_32x32x16_bf16 v[32:47], v[192:195], v[60:63], v[32:47]
	v_mfma_f32_32x32x16_bf16 v[48:63], v[48:51], v[52:55], 0
	v_mfma_f32_32x32x16_bf16 v[48:63], v[150:153], v[200:203], v[48:63]
	v_mfma_f32_32x32x16_bf16 v[48:63], v[158:161], v[206:209], v[48:63]
	v_mfma_f32_32x32x16_bf16 v[48:63], v[192:195], v[210:213], v[48:63]
	v_readlane_b32 s4, v255, 23
	v_readlane_b32 s5, v255, 24
	s_andn2_b64 vcc, exec, s[4:5]
	s_cbranch_vccnz .LBB0_1114
	v_subrev_u32_e32 v129, 64, v173
	s_mov_b32 s0, 0x100000
	v_cmp_gt_u32_e32 vcc, s0, v129
	v_add_u32_e32 v129, 0xffffffa0, v173
	s_nop 0
	v_cndmask_b32_e32 v64, v196, v64, vcc
	v_cmp_gt_u32_e32 vcc, s0, v129
	v_add_u32_e32 v129, 0xffffffbf, v173
	s_nop 0
	v_cndmask_b32_e32 v80, v196, v80, vcc
	v_cmp_gt_u32_e32 vcc, s0, v129
	v_add_u32_e32 v129, 0xffffff9f, v173
	s_nop 0
	v_cndmask_b32_e32 v65, v196, v65, vcc
	v_cmp_gt_u32_e32 vcc, s0, v129
	v_add_u32_e32 v129, 0xffffffbe, v173
	s_nop 0
	v_cndmask_b32_e32 v81, v196, v81, vcc
	v_cmp_gt_u32_e32 vcc, s0, v129
	v_add_u32_e32 v129, 0xffffff9e, v173
	s_nop 0
	v_cndmask_b32_e32 v66, v196, v66, vcc
	v_cmp_gt_u32_e32 vcc, s0, v129
	v_add_u32_e32 v129, 0xffffffbd, v173
	s_nop 0
	v_cndmask_b32_e32 v82, v196, v82, vcc
	v_cmp_gt_u32_e32 vcc, s0, v129
	v_add_u32_e32 v129, 0xffffff9d, v173
	s_nop 0
	v_cndmask_b32_e32 v67, v196, v67, vcc
	v_cmp_gt_u32_e32 vcc, s0, v129
	v_add_u32_e32 v129, 0xffffffb8, v173
	s_nop 0
	v_cndmask_b32_e32 v83, v196, v83, vcc
	v_cmp_gt_u32_e32 vcc, s0, v129
	v_add_u32_e32 v129, 0xffffff98, v173
	s_nop 0
	v_cndmask_b32_e32 v68, v196, v68, vcc
	v_cmp_gt_u32_e32 vcc, s0, v129
	v_add_u32_e32 v129, 0xffffffb7, v173
	s_nop 0
	v_cndmask_b32_e32 v84, v196, v84, vcc
	v_cmp_gt_u32_e32 vcc, s0, v129
	v_add_u32_e32 v129, 0xffffff97, v173
	s_nop 0
	v_cndmask_b32_e32 v69, v196, v69, vcc
	v_cmp_gt_u32_e32 vcc, s0, v129
	v_add_u32_e32 v129, 0xffffffb6, v173
	s_nop 0
	v_cndmask_b32_e32 v85, v196, v85, vcc
	v_cmp_gt_u32_e32 vcc, s0, v129
	v_add_u32_e32 v129, 0xffffff96, v173
	s_nop 0
	v_cndmask_b32_e32 v70, v196, v70, vcc
	v_cmp_gt_u32_e32 vcc, s0, v129
	v_add_u32_e32 v129, 0xffffffb5, v173
	s_nop 0
	v_cndmask_b32_e32 v86, v196, v86, vcc
	v_cmp_gt_u32_e32 vcc, s0, v129
	v_add_u32_e32 v129, 0xffffff95, v173
	s_nop 0
	v_cndmask_b32_e32 v71, v196, v71, vcc
	v_cmp_gt_u32_e32 vcc, s0, v129
	v_add_u32_e32 v129, 0xffffffb0, v173
	s_nop 0
	v_cndmask_b32_e32 v87, v196, v87, vcc
	v_cmp_gt_u32_e32 vcc, s0, v129
	v_add_u32_e32 v129, 0xffffff90, v173
	s_nop 0
	v_cndmask_b32_e32 v72, v196, v72, vcc
	v_cmp_gt_u32_e32 vcc, s0, v129
	v_add_u32_e32 v129, 0xffffffaf, v173
	s_nop 0
	v_cndmask_b32_e32 v88, v196, v88, vcc
	v_cmp_gt_u32_e32 vcc, s0, v129
	v_add_u32_e32 v129, 0xffffff8f, v173
	s_nop 0
	v_cndmask_b32_e32 v73, v196, v73, vcc
	v_cmp_gt_u32_e32 vcc, s0, v129
	v_add_u32_e32 v129, 0xffffffae, v173
	s_nop 0
	v_cndmask_b32_e32 v89, v196, v89, vcc
	v_cmp_gt_u32_e32 vcc, s0, v129
	v_add_u32_e32 v129, 0xffffff8e, v173
	s_nop 0
	v_cndmask_b32_e32 v74, v196, v74, vcc
	v_cmp_gt_u32_e32 vcc, s0, v129
	v_add_u32_e32 v129, 0xffffffad, v173
	s_nop 0
	v_cndmask_b32_e32 v90, v196, v90, vcc
	v_cmp_gt_u32_e32 vcc, s0, v129
	v_add_u32_e32 v129, 0xffffff8d, v173
	s_nop 0
	v_cndmask_b32_e32 v75, v196, v75, vcc
	v_cmp_gt_u32_e32 vcc, s0, v129
	v_add_u32_e32 v129, 0xffffffa8, v173
	s_nop 0
	v_cndmask_b32_e32 v91, v196, v91, vcc
	v_cmp_gt_u32_e32 vcc, s0, v129
	v_add_u32_e32 v129, 0xffffff88, v173
	s_nop 0
	v_cndmask_b32_e32 v76, v196, v76, vcc
	v_cmp_gt_u32_e32 vcc, s0, v129
	v_add_u32_e32 v129, 0xffffffa7, v173
	s_nop 0
	v_cndmask_b32_e32 v92, v196, v92, vcc
	v_cmp_gt_u32_e32 vcc, s0, v129
	v_add_u32_e32 v129, 0xffffff87, v173
	s_nop 0
	v_cndmask_b32_e32 v77, v196, v77, vcc
	v_cmp_gt_u32_e32 vcc, s0, v129
	v_add_u32_e32 v129, 0xffffffa6, v173
	s_nop 0
	v_cndmask_b32_e32 v93, v196, v93, vcc
	v_cmp_gt_u32_e32 vcc, s0, v129
	v_add_u32_e32 v129, 0xffffff86, v173
	s_nop 0
	v_cndmask_b32_e32 v78, v196, v78, vcc
	v_cmp_gt_u32_e32 vcc, s0, v129
	v_add_u32_e32 v129, 0xffffffa5, v173
	s_nop 0
	v_cndmask_b32_e32 v94, v196, v94, vcc
	v_cmp_gt_u32_e32 vcc, s0, v129
	v_add_u32_e32 v129, 0xffffff85, v173
	s_nop 0
	v_cndmask_b32_e32 v79, v196, v79, vcc
	v_cmp_gt_u32_e32 vcc, s0, v129
	s_nop 1
	v_cndmask_b32_e32 v95, v196, v95, vcc

.LBB0_1119:
	v_exp_f32_e32 v213, v64
	v_exp_f32_e32 v215, v65
	v_exp_f32_e32 v211, v66
	v_exp_f32_e32 v214, v67
	v_exp_f32_e32 v209, v68
	v_exp_f32_e32 v212, v69
	v_exp_f32_e32 v208, v70
	v_exp_f32_e32 v210, v71
	v_exp_f32_e32 v205, v72
	v_exp_f32_e32 v207, v73
	v_exp_f32_e32 v202, v74
	v_exp_f32_e32 v206, v75
	v_exp_f32_e32 v200, v76
	v_exp_f32_e32 v203, v77
	v_exp_f32_e32 v199, v78
	v_exp_f32_e32 v201, v79
	s_waitcnt lgkmcnt(0)
	s_barrier
	v_lshlrev_b64 v[64:65], 8, v[166:167]
	s_mov_b64 s[4:5], 0xc000
	v_lshl_add_u64 v[66:67], v[64:65], 0, s[4:5]
	s_mov_b64 s[4:5], 0xe000
	v_lshl_add_u64 v[68:69], v[148:149], 0, v[66:67]
	v_lshl_add_u64 v[64:65], v[64:65], 0, s[4:5]
	v_lshl_add_u64 v[66:67], v[156:157], 0, v[66:67]
	v_lshl_add_u64 v[70:71], v[148:149], 0, v[64:65]
	global_load_dwordx4 v[148:151], v[68:69], off
	global_load_dwordx4 v[152:155], v[70:71], off
	v_lshl_add_u64 v[64:65], v[156:157], 0, v[64:65]
	global_load_dwordx4 v[156:159], v[66:67], off
	global_load_dwordx4 v[160:163], v[64:65], off
	ds_read2_b64 v[64:67], v198 offset0:128 offset1:160
	v_mov_b64_e32 v[70:71], s[10:11]
	v_mov_b64_e32 v[74:75], s[10:11]
	v_mov_b64_e32 v[68:69], s[8:9]
	v_mov_b64_e32 v[72:73], s[8:9]
	s_waitcnt lgkmcnt(0)
	v_or_b32_e32 v69, 1.0, v65
	v_mov_b32_e32 v68, v64
	v_or_b32_e32 v73, 1.0, v67
	v_mov_b32_e32 v72, v66
	v_cndmask_b32_e64 v129, 0, v189, s[6:7]
	v_mov_b64_e32 v[76:77], v[128:129]
	v_cndmask_b32_e64 v64, 0, v197, s[6:7]
	v_mov_b64_e32 v[78:79], v[130:131]
	v_mov_b32_e32 v78, v64
	s_nop 1
	v_mfma_f32_32x32x16_bf16 v[96:111], v[68:71], v[76:79], 0
	v_mfma_f32_32x32x16_bf16 v[64:79], v[72:75], v[76:79], 0
	ds_read_b128 v[192:195], v181 offset:32768
	ds_read_b128 v[216:219], v181 offset:40960
	ds_read_b128 v[220:223], v180 offset:32768
	s_waitcnt lgkmcnt(2)
	v_mfma_f32_32x32x16_bf16 v[96:111], v[192:195], v[144:147], v[96:111]
	ds_read_b128 v[192:195], v180 offset:40960
	s_waitcnt lgkmcnt(2)
	v_mfma_f32_32x32x16_bf16 v[64:79], v[216:219], v[144:147], v[64:79]
	ds_read_b128 v[216:219], v179 offset:32768
	s_waitcnt lgkmcnt(2)
	v_mfma_f32_32x32x16_bf16 v[96:111], v[220:223], v[140:143], v[96:111]
	ds_read_b128 v[220:223], v179 offset:40960
	s_waitcnt lgkmcnt(2)
	v_mfma_f32_32x32x16_bf16 v[64:79], v[192:195], v[140:143], v[64:79]
	ds_read_b128 v[192:195], v169 offset:32768
	s_waitcnt lgkmcnt(2)
	v_mfma_f32_32x32x16_bf16 v[96:111], v[216:219], v[136:139], v[96:111]
	ds_read_b128 v[216:219], v169 offset:40960
	s_waitcnt lgkmcnt(2)
	v_mfma_f32_32x32x16_bf16 v[64:79], v[220:223], v[136:139], v[64:79]
	ds_read_b128 v[220:223], v181 offset:32896
	s_waitcnt lgkmcnt(2)
	v_mfma_f32_32x32x16_bf16 v[96:111], v[192:195], v[132:135], v[96:111]
	ds_read_b128 v[192:195], v181 offset:41088
	s_waitcnt lgkmcnt(2)
	v_mfma_f32_32x32x16_bf16 v[64:79], v[216:219], v[132:135], v[64:79]
	ds_read_b128 v[216:219], v180 offset:32896
	s_waitcnt lgkmcnt(2)
	v_mfma_f32_32x32x16_bf16 v[96:111], v[220:223], v[124:127], v[96:111]
	ds_read_b128 v[220:223], v180 offset:41088
	s_waitcnt lgkmcnt(2)
	v_mfma_f32_32x32x16_bf16 v[64:79], v[192:195], v[124:127], v[64:79]
	ds_read_b128 v[192:195], v179 offset:32896
	s_waitcnt lgkmcnt(2)
	v_mfma_f32_32x32x16_bf16 v[96:111], v[216:219], v[120:123], v[96:111]
	ds_read_b128 v[216:219], v179 offset:41088
	s_waitcnt lgkmcnt(2)
	v_mfma_f32_32x32x16_bf16 v[64:79], v[220:223], v[120:123], v[64:79]
	ds_read_b128 v[220:223], v169 offset:32896
	s_waitcnt lgkmcnt(2)
	v_mfma_f32_32x32x16_bf16 v[96:111], v[192:195], v[116:119], v[96:111]
	ds_read_b128 v[192:195], v169 offset:41088
	s_waitcnt lgkmcnt(2)
	v_mfma_f32_32x32x16_bf16 v[64:79], v[216:219], v[116:119], v[64:79]
	s_waitcnt lgkmcnt(1)
	v_mfma_f32_32x32x16_bf16 v[96:111], v[220:223], v[112:115], v[96:111]
	s_waitcnt lgkmcnt(0)
	v_mfma_f32_32x32x16_bf16 v[64:79], v[192:195], v[112:115], v[64:79]
	v_exp_f32_e32 v129, v80
	v_add_f32_e32 v80, 0, v213
	v_add_f32_e32 v80, v215, v80
	v_add_f32_e32 v80, v211, v80
	v_add_f32_e32 v80, v214, v80
	v_add_f32_e32 v80, v209, v80
	v_add_f32_e32 v80, v212, v80
	v_add_f32_e32 v80, v208, v80
	v_add_f32_e32 v80, v210, v80
	v_add_f32_e32 v80, v205, v80
	v_add_f32_e32 v80, v207, v80
	v_add_f32_e32 v80, v202, v80
	v_add_f32_e32 v80, v206, v80
	v_add_f32_e32 v80, v200, v80
	v_exp_f32_e32 v192, v81
	v_add_f32_e32 v80, v203, v80
	v_exp_f32_e32 v193, v82
	v_add_f32_e32 v80, v199, v80
	v_exp_f32_e32 v194, v83
	v_add_f32_e32 v80, v201, v80
	v_exp_f32_e32 v195, v84
	v_add_f32_e32 v80, v129, v80
	v_exp_f32_e32 v216, v85
	v_add_f32_e32 v80, v192, v80
	v_exp_f32_e32 v217, v86
	v_add_f32_e32 v80, v193, v80
	v_exp_f32_e32 v218, v87
	v_add_f32_e32 v80, v194, v80
	v_exp_f32_e32 v219, v88
	v_add_f32_e32 v80, v195, v80
	v_exp_f32_e32 v220, v89
	v_add_f32_e32 v80, v216, v80
	v_exp_f32_e32 v221, v90
	v_add_f32_e32 v80, v217, v80
	v_exp_f32_e32 v222, v91
	v_add_f32_e32 v80, v218, v80
	v_exp_f32_e32 v223, v92
	v_add_f32_e32 v80, v219, v80
	v_exp_f32_e32 v224, v93
	v_add_f32_e32 v80, v220, v80
	v_exp_f32_e32 v225, v94
	v_add_f32_e32 v80, v221, v80
	v_exp_f32_e32 v95, v95
	v_add_f32_e32 v80, v222, v80
	v_add_f32_e32 v80, v223, v80
	v_add_f32_e32 v80, v224, v80
	v_add_f32_e32 v80, v225, v80
	v_add_f32_e32 v187, v95, v80
	v_mov_b32_e32 v188, v187
	s_nop 1
	v_permlane32_swap_b32_e32 v187, v188
	v_cvt_pk_bf16_f32 v80, v213, v215
	v_cvt_pk_bf16_f32 v81, v211, v214
	v_cvt_pk_bf16_f32 v82, v209, v212
	v_cvt_pk_bf16_f32 v83, v208, v210
	v_cvt_pk_bf16_f32 v84, v205, v207
	v_cvt_pk_bf16_f32 v85, v202, v206
	v_cvt_pk_bf16_f32 v86, v200, v203
	v_cvt_pk_bf16_f32 v87, v199, v201
	v_cvt_pk_bf16_f32 v88, v129, v192
	v_cvt_pk_bf16_f32 v89, v193, v194
	v_cvt_pk_bf16_f32 v90, v195, v216
	v_cvt_pk_bf16_f32 v91, v217, v218
	v_cvt_pk_bf16_f32 v92, v219, v220
	v_cvt_pk_bf16_f32 v93, v221, v222
	v_cvt_pk_bf16_f32 v94, v223, v224
	v_cvt_pk_bf16_f32 v95, v225, v95
	s_nop 0
	v_permlane32_swap_b32_e32 v80, v82
	v_permlane32_swap_b32_e32 v81, v83
	v_permlane32_swap_b32_e32 v84, v86
	v_permlane32_swap_b32_e32 v85, v87
	v_permlane32_swap_b32_e32 v88, v90
	v_permlane32_swap_b32_e32 v89, v91
	v_permlane32_swap_b32_e32 v92, v94
	v_permlane32_swap_b32_e32 v93, v95
	ds_read_b64_tr_b16 v[192:193], v175 offset:0x4000
	ds_read_b64_tr_b16 v[194:195], v175 offset:0x4800
	ds_read_b64_tr_b16 v[200:201], v175 offset:0x5000
	ds_read_b64_tr_b16 v[202:203], v175 offset:0x5800
	ds_read_b64_tr_b16 v[206:207], v175 offset:0x6000
	ds_read_b64_tr_b16 v[208:209], v175 offset:0x6800
	ds_read_b64_tr_b16 v[210:211], v175 offset:0x7000
	ds_read_b64_tr_b16 v[212:213], v175 offset:0x7800
	s_waitcnt lgkmcnt(0)
	s_nop 0
	v_mfma_f32_32x32x16_bf16 v[0:15], v[80:83], v[192:195], v[0:15]
	ds_read_b64_tr_b16 v[192:193], v175 offset:0x4200
	ds_read_b64_tr_b16 v[194:195], v175 offset:0x4a00
	v_mfma_f32_32x32x16_bf16 v[0:15], v[84:87], v[200:203], v[0:15]
	ds_read_b64_tr_b16 v[200:201], v175 offset:0x5200
	ds_read_b64_tr_b16 v[202:203], v175 offset:0x5a00
	v_mfma_f32_32x32x16_bf16 v[0:15], v[88:91], v[206:209], v[0:15]
	ds_read_b64_tr_b16 v[206:207], v175 offset:0x6200
	ds_read_b64_tr_b16 v[208:209], v175 offset:0x6a00
	v_mfma_f32_32x32x16_bf16 v[0:15], v[92:95], v[210:213], v[0:15]
	ds_read_b64_tr_b16 v[210:211], v175 offset:0x7200
	ds_read_b64_tr_b16 v[212:213], v175 offset:0x7a00
	s_waitcnt lgkmcnt(0)
	v_mfma_f32_32x32x16_bf16 v[16:31], v[80:83], v[192:195], v[16:31]
	ds_read_b64_tr_b16 v[192:193], v175 offset:0x4400
	ds_read_b64_tr_b16 v[194:195], v175 offset:0x4c00
	v_mfma_f32_32x32x16_bf16 v[16:31], v[84:87], v[200:203], v[16:31]
	ds_read_b64_tr_b16 v[200:201], v175 offset:0x5400
	ds_read_b64_tr_b16 v[202:203], v175 offset:0x5c00
	v_mfma_f32_32x32x16_bf16 v[16:31], v[88:91], v[206:209], v[16:31]
	ds_read_b64_tr_b16 v[206:207], v175 offset:0x6400
	ds_read_b64_tr_b16 v[208:209], v175 offset:0x6c00
	v_mfma_f32_32x32x16_bf16 v[16:31], v[92:95], v[210:213], v[16:31]
	ds_read_b64_tr_b16 v[210:211], v175 offset:0x7400
	ds_read_b64_tr_b16 v[212:213], v175 offset:0x7c00
	s_waitcnt lgkmcnt(0)
	v_mfma_f32_32x32x16_bf16 v[32:47], v[80:83], v[192:195], v[32:47]
	ds_read_b64_tr_b16 v[192:193], v175 offset:0x4600
	ds_read_b64_tr_b16 v[194:195], v175 offset:0x4e00
	v_mfma_f32_32x32x16_bf16 v[32:47], v[84:87], v[200:203], v[32:47]
	ds_read_b64_tr_b16 v[200:201], v175 offset:0x5600
	ds_read_b64_tr_b16 v[202:203], v175 offset:0x5e00
	v_mfma_f32_32x32x16_bf16 v[32:47], v[88:91], v[206:209], v[32:47]
	ds_read_b64_tr_b16 v[206:207], v175 offset:0x6600
	ds_read_b64_tr_b16 v[208:209], v175 offset:0x6e00
	v_mfma_f32_32x32x16_bf16 v[32:47], v[92:95], v[210:213], v[32:47]
	ds_read_b64_tr_b16 v[210:211], v175 offset:0x7600
	ds_read_b64_tr_b16 v[212:213], v175 offset:0x7e00
	s_waitcnt lgkmcnt(0)
	v_mfma_f32_32x32x16_bf16 v[48:63], v[80:83], v[192:195], v[48:63]
	v_mfma_f32_32x32x16_bf16 v[48:63], v[84:87], v[200:203], v[48:63]
	v_mfma_f32_32x32x16_bf16 v[48:63], v[88:91], v[206:209], v[48:63]
	v_mfma_f32_32x32x16_bf16 v[48:63], v[92:95], v[210:213], v[48:63]
	v_readlane_b32 s4, v255, 25
	v_readlane_b32 s5, v255, 26
	s_andn2_b64 vcc, exec, s[4:5]
	s_cbranch_vccnz .LBB0_1121
	v_add_u32_e32 v80, 0xffffff80, v173
	s_mov_b32 s0, 0x100000
	v_cmp_gt_u32_e32 vcc, s0, v80
	v_add_u32_e32 v80, 0xffffff60, v173
	s_nop 0
	v_cndmask_b32_e32 v96, v196, v96, vcc
	v_cmp_gt_u32_e32 vcc, s0, v80
	v_add_u32_e32 v80, 0xffffff7f, v173
	s_nop 0
	v_cndmask_b32_e32 v64, v196, v64, vcc
	v_cmp_gt_u32_e32 vcc, s0, v80
	v_add_u32_e32 v80, 0xffffff5f, v173
	s_nop 0
	v_cndmask_b32_e32 v97, v196, v97, vcc
	v_cmp_gt_u32_e32 vcc, s0, v80
	v_add_u32_e32 v80, 0xffffff7e, v173
	s_nop 0
	v_cndmask_b32_e32 v65, v196, v65, vcc
	v_cmp_gt_u32_e32 vcc, s0, v80
	v_add_u32_e32 v80, 0xffffff5e, v173
	s_nop 0
	v_cndmask_b32_e32 v98, v196, v98, vcc
	v_cmp_gt_u32_e32 vcc, s0, v80
	v_add_u32_e32 v80, 0xffffff7d, v173
	s_nop 0
	v_cndmask_b32_e32 v66, v196, v66, vcc
	v_cmp_gt_u32_e32 vcc, s0, v80
	v_add_u32_e32 v80, 0xffffff5d, v173
	s_nop 0
	v_cndmask_b32_e32 v99, v196, v99, vcc
	v_cmp_gt_u32_e32 vcc, s0, v80
	v_add_u32_e32 v80, 0xffffff78, v173
	s_nop 0
	v_cndmask_b32_e32 v67, v196, v67, vcc
	v_cmp_gt_u32_e32 vcc, s0, v80
	v_add_u32_e32 v80, 0xffffff58, v173
	s_nop 0
	v_cndmask_b32_e32 v100, v196, v100, vcc
	v_cmp_gt_u32_e32 vcc, s0, v80
	v_add_u32_e32 v80, 0xffffff77, v173
	s_nop 0
	v_cndmask_b32_e32 v68, v196, v68, vcc
	v_cmp_gt_u32_e32 vcc, s0, v80
	v_add_u32_e32 v80, 0xffffff57, v173
	s_nop 0
	v_cndmask_b32_e32 v101, v196, v101, vcc
	v_cmp_gt_u32_e32 vcc, s0, v80
	v_add_u32_e32 v80, 0xffffff76, v173
	s_nop 0
	v_cndmask_b32_e32 v69, v196, v69, vcc
	v_cmp_gt_u32_e32 vcc, s0, v80
	v_add_u32_e32 v80, 0xffffff56, v173
	s_nop 0
	v_cndmask_b32_e32 v102, v196, v102, vcc
	v_cmp_gt_u32_e32 vcc, s0, v80
	v_add_u32_e32 v80, 0xffffff75, v173
	s_nop 0
	v_cndmask_b32_e32 v70, v196, v70, vcc
	v_cmp_gt_u32_e32 vcc, s0, v80
	v_add_u32_e32 v80, 0xffffff55, v173
	s_nop 0
	v_cndmask_b32_e32 v103, v196, v103, vcc
	v_cmp_gt_u32_e32 vcc, s0, v80
	v_add_u32_e32 v80, 0xffffff70, v173
	s_nop 0
	v_cndmask_b32_e32 v71, v196, v71, vcc
	v_cmp_gt_u32_e32 vcc, s0, v80
	v_add_u32_e32 v80, 0xffffff50, v173
	s_nop 0
	v_cndmask_b32_e32 v104, v196, v104, vcc
	v_cmp_gt_u32_e32 vcc, s0, v80
	v_add_u32_e32 v80, 0xffffff6f, v173
	s_nop 0
	v_cndmask_b32_e32 v72, v196, v72, vcc
	v_cmp_gt_u32_e32 vcc, s0, v80
	v_add_u32_e32 v80, 0xffffff4f, v173
	s_nop 0
	v_cndmask_b32_e32 v105, v196, v105, vcc
	v_cmp_gt_u32_e32 vcc, s0, v80
	v_add_u32_e32 v80, 0xffffff6e, v173
	s_nop 0
	v_cndmask_b32_e32 v73, v196, v73, vcc
	v_cmp_gt_u32_e32 vcc, s0, v80
	v_add_u32_e32 v80, 0xffffff4e, v173
	s_nop 0
	v_cndmask_b32_e32 v106, v196, v106, vcc
	v_cmp_gt_u32_e32 vcc, s0, v80
	v_add_u32_e32 v80, 0xffffff6d, v173
	s_nop 0
	v_cndmask_b32_e32 v74, v196, v74, vcc
	v_cmp_gt_u32_e32 vcc, s0, v80
	v_add_u32_e32 v80, 0xffffff4d, v173
	s_nop 0
	v_cndmask_b32_e32 v107, v196, v107, vcc
	v_cmp_gt_u32_e32 vcc, s0, v80
	v_add_u32_e32 v80, 0xffffff68, v173
	s_nop 0
	v_cndmask_b32_e32 v75, v196, v75, vcc
	v_cmp_gt_u32_e32 vcc, s0, v80
	v_add_u32_e32 v80, 0xffffff48, v173
	s_nop 0
	v_cndmask_b32_e32 v108, v196, v108, vcc
	v_cmp_gt_u32_e32 vcc, s0, v80
	v_add_u32_e32 v80, 0xffffff67, v173
	s_nop 0
	v_cndmask_b32_e32 v76, v196, v76, vcc
	v_cmp_gt_u32_e32 vcc, s0, v80
	v_add_u32_e32 v80, 0xffffff47, v173
	s_nop 0
	v_cndmask_b32_e32 v109, v196, v109, vcc
	v_cmp_gt_u32_e32 vcc, s0, v80
	v_add_u32_e32 v80, 0xffffff66, v173
	s_nop 0
	v_cndmask_b32_e32 v77, v196, v77, vcc
	v_cmp_gt_u32_e32 vcc, s0, v80
	v_add_u32_e32 v80, 0xffffff46, v173
	s_nop 0
	v_cndmask_b32_e32 v110, v196, v110, vcc
	v_cmp_gt_u32_e32 vcc, s0, v80
	v_add_u32_e32 v80, 0xffffff65, v173
	s_nop 0
	v_cndmask_b32_e32 v78, v196, v78, vcc
	v_cmp_gt_u32_e32 vcc, s0, v80
	v_add_u32_e32 v80, 0xffffff45, v173
	s_nop 0
	v_cndmask_b32_e32 v111, v196, v111, vcc
	v_cmp_gt_u32_e32 vcc, s0, v80
	s_nop 1
	v_cndmask_b32_e32 v79, v196, v79, vcc

.LBB0_1126:
	v_exp_f32_e32 v161, v96
	v_exp_f32_e32 v163, v97
	v_exp_f32_e32 v159, v98
	v_exp_f32_e32 v162, v99
	v_exp_f32_e32 v157, v100
	v_exp_f32_e32 v160, v101
	v_exp_f32_e32 v156, v102
	v_exp_f32_e32 v158, v103
	v_exp_f32_e32 v153, v104
	v_exp_f32_e32 v155, v105
	v_exp_f32_e32 v151, v106
	v_exp_f32_e32 v154, v107
	v_exp_f32_e32 v149, v108
	v_exp_f32_e32 v152, v109
	v_exp_f32_e32 v148, v110
	v_exp_f32_e32 v150, v111
	s_waitcnt lgkmcnt(0)
	s_barrier
	ds_read2_b64 v[80:83], v198 offset0:192 offset1:224
	v_mov_b64_e32 v[86:87], s[10:11]
	v_mov_b64_e32 v[90:91], s[10:11]
	v_mov_b64_e32 v[84:85], s[8:9]
	v_mov_b64_e32 v[88:89], s[8:9]
	s_waitcnt lgkmcnt(0)
	v_or_b32_e32 v85, 1.0, v81
	v_mov_b32_e32 v84, v80
	v_or_b32_e32 v89, 1.0, v83
	v_mov_b32_e32 v88, v82
	v_cndmask_b32_e64 v129, 0, v189, s[6:7]
	v_mov_b64_e32 v[92:93], v[128:129]
	v_cndmask_b32_e64 v80, 0, v197, s[6:7]
	v_mov_b64_e32 v[94:95], v[130:131]
	v_mov_b32_e32 v94, v80
	s_nop 1
	v_mfma_f32_32x32x16_bf16 v[96:111], v[84:87], v[92:95], 0
	v_mfma_f32_32x32x16_bf16 v[80:95], v[88:91], v[92:95], 0
	ds_read_b128 v[192:195], v181 offset:49152
	s_waitcnt lgkmcnt(0)
	v_mfma_f32_32x32x16_bf16 v[96:111], v[192:195], v[144:147], v[96:111]
	ds_read_b128 v[192:195], v181 offset:57344
	s_waitcnt lgkmcnt(0)
	v_mfma_f32_32x32x16_bf16 v[80:95], v[192:195], v[144:147], v[80:95]
	ds_read_b128 v[144:147], v180 offset:49152
	s_waitcnt lgkmcnt(0)
	v_mfma_f32_32x32x16_bf16 v[96:111], v[144:147], v[140:143], v[96:111]
	ds_read_b128 v[144:147], v180 offset:57344
	s_waitcnt lgkmcnt(0)
	v_mfma_f32_32x32x16_bf16 v[80:95], v[144:147], v[140:143], v[80:95]
	ds_read_b128 v[140:143], v179 offset:49152
	s_waitcnt lgkmcnt(0)
	v_mfma_f32_32x32x16_bf16 v[96:111], v[140:143], v[136:139], v[96:111]
	ds_read_b128 v[140:143], v179 offset:57344
	s_waitcnt lgkmcnt(0)
	v_mfma_f32_32x32x16_bf16 v[80:95], v[140:143], v[136:139], v[80:95]
	ds_read_b128 v[136:139], v169 offset:49152
	s_waitcnt lgkmcnt(0)
	v_mfma_f32_32x32x16_bf16 v[96:111], v[136:139], v[132:135], v[96:111]
	ds_read_b128 v[136:139], v169 offset:57344
	s_waitcnt lgkmcnt(0)
	v_mfma_f32_32x32x16_bf16 v[80:95], v[136:139], v[132:135], v[80:95]
	ds_read_b128 v[132:135], v181 offset:49280
	s_waitcnt lgkmcnt(0)
	v_mfma_f32_32x32x16_bf16 v[96:111], v[132:135], v[124:127], v[96:111]
	ds_read_b128 v[132:135], v181 offset:57472
	s_waitcnt lgkmcnt(0)
	v_mfma_f32_32x32x16_bf16 v[80:95], v[132:135], v[124:127], v[80:95]
	ds_read_b128 v[124:127], v180 offset:49280
	s_waitcnt lgkmcnt(0)
	v_mfma_f32_32x32x16_bf16 v[96:111], v[124:127], v[120:123], v[96:111]
	ds_read_b128 v[124:127], v180 offset:57472
	s_waitcnt lgkmcnt(0)
	v_mfma_f32_32x32x16_bf16 v[80:95], v[124:127], v[120:123], v[80:95]
	ds_read_b128 v[120:123], v179 offset:49280
	s_waitcnt lgkmcnt(0)
	v_mfma_f32_32x32x16_bf16 v[96:111], v[120:123], v[116:119], v[96:111]
	ds_read_b128 v[120:123], v179 offset:57472
	s_waitcnt lgkmcnt(0)
	v_mfma_f32_32x32x16_bf16 v[80:95], v[120:123], v[116:119], v[80:95]
	ds_read_b128 v[116:119], v169 offset:49280
	s_waitcnt lgkmcnt(0)
	v_mfma_f32_32x32x16_bf16 v[96:111], v[116:119], v[112:115], v[96:111]
	ds_read_b128 v[116:119], v169 offset:57472
	s_waitcnt lgkmcnt(0)
	v_mfma_f32_32x32x16_bf16 v[80:95], v[116:119], v[112:115], v[80:95]
	v_ashrrev_i32_e32 v169, 31, v168
	v_lshlrev_b64 v[112:113], 8, v[166:167]
	v_lshlrev_b64 v[114:115], 8, v[168:169]
	v_lshl_add_u64 v[112:113], s[72:73], 0, v[112:113]
	v_lshl_add_u64 v[114:115], s[72:73], 0, v[114:115]
	v_lshl_add_u64 v[112:113], v[112:113], 0, v[130:131]
	v_lshl_add_u64 v[116:117], v[114:115], 0, v[130:131]
	global_load_dwordx4 v[112:115], v[112:113], off
	s_nop 0
	global_load_dwordx4 v[116:119], v[116:117], off
	v_exp_f32_e32 v120, v64
	v_add_f32_e32 v64, 0, v161
	v_add_f32_e32 v64, v163, v64
	v_add_f32_e32 v64, v159, v64
	v_add_f32_e32 v64, v162, v64
	v_add_f32_e32 v64, v157, v64
	v_add_f32_e32 v64, v160, v64
	v_add_f32_e32 v64, v156, v64
	v_add_f32_e32 v64, v158, v64
	v_add_f32_e32 v64, v153, v64
	v_add_f32_e32 v64, v155, v64
	v_add_f32_e32 v64, v151, v64
	v_add_f32_e32 v64, v154, v64
	v_add_f32_e32 v64, v149, v64
	v_exp_f32_e32 v121, v65
	v_add_f32_e32 v64, v152, v64
	v_exp_f32_e32 v122, v66
	v_add_f32_e32 v64, v148, v64
	v_exp_f32_e32 v123, v67
	v_add_f32_e32 v64, v150, v64
	v_exp_f32_e32 v124, v68
	v_add_f32_e32 v64, v120, v64
	v_exp_f32_e32 v125, v69
	v_add_f32_e32 v64, v121, v64
	v_exp_f32_e32 v126, v70
	v_add_f32_e32 v64, v122, v64
	v_exp_f32_e32 v127, v71
	v_add_f32_e32 v64, v123, v64
	v_exp_f32_e32 v128, v72
	v_add_f32_e32 v64, v124, v64
	v_exp_f32_e32 v129, v73
	v_add_f32_e32 v64, v125, v64
	v_exp_f32_e32 v130, v74
	v_add_f32_e32 v64, v126, v64
	v_exp_f32_e32 v132, v75
	v_add_f32_e32 v64, v127, v64
	v_exp_f32_e32 v133, v76
	v_add_f32_e32 v64, v128, v64
	v_exp_f32_e32 v134, v77
	v_add_f32_e32 v64, v129, v64
	v_exp_f32_e32 v78, v78
	v_add_f32_e32 v64, v130, v64
	v_exp_f32_e32 v79, v79
	v_add_f32_e32 v64, v132, v64
	v_add_f32_e32 v64, v133, v64
	v_add_f32_e32 v64, v134, v64
	v_add_f32_e32 v64, v78, v64
	v_add_f32_e32 v72, v79, v64
	v_mov_b32_e32 v73, v72
	s_nop 1
	v_permlane32_swap_b32_e32 v72, v73
	v_cvt_pk_bf16_f32 v64, v161, v163
	v_cvt_pk_bf16_f32 v65, v159, v162
	v_cvt_pk_bf16_f32 v66, v157, v160
	v_cvt_pk_bf16_f32 v67, v156, v158
	v_cvt_pk_bf16_f32 v68, v153, v155
	v_cvt_pk_bf16_f32 v69, v151, v154
	v_cvt_pk_bf16_f32 v70, v149, v152
	v_cvt_pk_bf16_f32 v71, v148, v150
	v_cvt_pk_bf16_f32 v74, v120, v121
	v_cvt_pk_bf16_f32 v75, v122, v123
	v_cvt_pk_bf16_f32 v76, v124, v125
	v_cvt_pk_bf16_f32 v77, v126, v127
	v_cvt_pk_bf16_f32 v120, v128, v129
	v_cvt_pk_bf16_f32 v121, v130, v132
	v_cvt_pk_bf16_f32 v122, v133, v134
	v_cvt_pk_bf16_f32 v123, v78, v79
	s_nop 0
	v_permlane32_swap_b32_e32 v64, v66
	v_permlane32_swap_b32_e32 v65, v67
	v_permlane32_swap_b32_e32 v68, v70
	v_permlane32_swap_b32_e32 v69, v71
	v_permlane32_swap_b32_e32 v74, v76
	v_permlane32_swap_b32_e32 v75, v77
	v_permlane32_swap_b32_e32 v120, v122
	v_permlane32_swap_b32_e32 v121, v123
	ds_read_b64_tr_b16 v[124:125], v175 offset:0
	ds_read_b64_tr_b16 v[126:127], v175 offset:0x800
	ds_read_b64_tr_b16 v[132:133], v175 offset:0x1000
	ds_read_b64_tr_b16 v[134:135], v175 offset:0x1800
	ds_read_b64_tr_b16 v[136:137], v175 offset:0x2000
	ds_read_b64_tr_b16 v[138:139], v175 offset:0x2800
	ds_read_b64_tr_b16 v[140:141], v175 offset:0x3000
	ds_read_b64_tr_b16 v[142:143], v175 offset:0x3800
	s_waitcnt lgkmcnt(0)
	s_nop 0
	v_mfma_f32_32x32x16_bf16 v[0:15], v[64:67], v[124:127], v[0:15]
	ds_read_b64_tr_b16 v[124:125], v175 offset:0x200
	ds_read_b64_tr_b16 v[126:127], v175 offset:0xa00
	v_mfma_f32_32x32x16_bf16 v[0:15], v[68:71], v[132:135], v[0:15]
	ds_read_b64_tr_b16 v[132:133], v175 offset:0x1200
	ds_read_b64_tr_b16 v[134:135], v175 offset:0x1a00
	v_mfma_f32_32x32x16_bf16 v[0:15], v[74:77], v[136:139], v[0:15]
	ds_read_b64_tr_b16 v[136:137], v175 offset:0x2200
	ds_read_b64_tr_b16 v[138:139], v175 offset:0x2a00
	v_mfma_f32_32x32x16_bf16 v[0:15], v[120:123], v[140:143], v[0:15]
	ds_read_b64_tr_b16 v[140:141], v175 offset:0x3200
	ds_read_b64_tr_b16 v[142:143], v175 offset:0x3a00
	s_waitcnt lgkmcnt(0)
	v_mfma_f32_32x32x16_bf16 v[16:31], v[64:67], v[124:127], v[16:31]
	ds_read_b64_tr_b16 v[124:125], v175 offset:0x400
	ds_read_b64_tr_b16 v[126:127], v175 offset:0xc00
	v_mfma_f32_32x32x16_bf16 v[16:31], v[68:71], v[132:135], v[16:31]
	ds_read_b64_tr_b16 v[132:133], v175 offset:0x1400
	ds_read_b64_tr_b16 v[134:135], v175 offset:0x1c00
	v_mfma_f32_32x32x16_bf16 v[16:31], v[74:77], v[136:139], v[16:31]
	ds_read_b64_tr_b16 v[136:137], v175 offset:0x2400
	ds_read_b64_tr_b16 v[138:139], v175 offset:0x2c00
	v_mfma_f32_32x32x16_bf16 v[16:31], v[120:123], v[140:143], v[16:31]
	ds_read_b64_tr_b16 v[140:141], v175 offset:0x3400
	ds_read_b64_tr_b16 v[142:143], v175 offset:0x3c00
	s_waitcnt lgkmcnt(0)
	v_mfma_f32_32x32x16_bf16 v[32:47], v[64:67], v[124:127], v[32:47]
	ds_read_b64_tr_b16 v[124:125], v175 offset:0x600
	ds_read_b64_tr_b16 v[126:127], v175 offset:0xe00
	v_mfma_f32_32x32x16_bf16 v[32:47], v[68:71], v[132:135], v[32:47]
	ds_read_b64_tr_b16 v[132:133], v175 offset:0x1600
	ds_read_b64_tr_b16 v[134:135], v175 offset:0x1e00
	v_mfma_f32_32x32x16_bf16 v[32:47], v[74:77], v[136:139], v[32:47]
	ds_read_b64_tr_b16 v[136:137], v175 offset:0x2600
	ds_read_b64_tr_b16 v[138:139], v175 offset:0x2e00
	v_mfma_f32_32x32x16_bf16 v[32:47], v[120:123], v[140:143], v[32:47]
	ds_read_b64_tr_b16 v[140:141], v175 offset:0x3600
	ds_read_b64_tr_b16 v[142:143], v175 offset:0x3e00
	s_waitcnt lgkmcnt(0)
	v_mfma_f32_32x32x16_bf16 v[48:63], v[64:67], v[124:127], v[48:63]
	v_mfma_f32_32x32x16_bf16 v[48:63], v[68:71], v[132:135], v[48:63]
	v_mfma_f32_32x32x16_bf16 v[48:63], v[74:77], v[136:139], v[48:63]
	v_mfma_f32_32x32x16_bf16 v[48:63], v[120:123], v[140:143], v[48:63]
	v_readlane_b32 s4, v255, 21
	v_readlane_b32 s5, v255, 22
	s_andn2_b64 vcc, exec, s[4:5]
	s_cbranch_vccnz .LBB0_1128
	v_add_u32_e32 v64, 0xffffff40, v173
	s_mov_b32 s0, 0x100000
	v_cmp_gt_u32_e32 vcc, s0, v64
	v_add_u32_e32 v64, 0xffffff20, v173
	s_nop 0
	v_cndmask_b32_e32 v96, v196, v96, vcc
	v_cmp_gt_u32_e32 vcc, s0, v64
	v_add_u32_e32 v64, 0xffffff3f, v173
	s_nop 0
	v_cndmask_b32_e32 v80, v196, v80, vcc
	v_cmp_gt_u32_e32 vcc, s0, v64
	v_add_u32_e32 v64, 0xffffff1f, v173
	s_nop 0
	v_cndmask_b32_e32 v97, v196, v97, vcc
	v_cmp_gt_u32_e32 vcc, s0, v64
	v_add_u32_e32 v64, 0xffffff3e, v173
	s_nop 0
	v_cndmask_b32_e32 v81, v196, v81, vcc
	v_cmp_gt_u32_e32 vcc, s0, v64
	v_add_u32_e32 v64, 0xffffff1e, v173
	s_nop 0
	v_cndmask_b32_e32 v98, v196, v98, vcc
	v_cmp_gt_u32_e32 vcc, s0, v64
	v_add_u32_e32 v64, 0xffffff3d, v173
	s_nop 0
	v_cndmask_b32_e32 v82, v196, v82, vcc
	v_cmp_gt_u32_e32 vcc, s0, v64
	v_add_u32_e32 v64, 0xffffff1d, v173
	s_nop 0
	v_cndmask_b32_e32 v99, v196, v99, vcc
	v_cmp_gt_u32_e32 vcc, s0, v64
	v_add_u32_e32 v64, 0xffffff38, v173
	s_nop 0
	v_cndmask_b32_e32 v83, v196, v83, vcc
	v_cmp_gt_u32_e32 vcc, s0, v64
	v_add_u32_e32 v64, 0xffffff18, v173
	s_nop 0
	v_cndmask_b32_e32 v100, v196, v100, vcc
	v_cmp_gt_u32_e32 vcc, s0, v64
	v_add_u32_e32 v64, 0xffffff37, v173
	s_nop 0
	v_cndmask_b32_e32 v84, v196, v84, vcc
	v_cmp_gt_u32_e32 vcc, s0, v64
	v_add_u32_e32 v64, 0xffffff17, v173
	s_nop 0
	v_cndmask_b32_e32 v101, v196, v101, vcc
	v_cmp_gt_u32_e32 vcc, s0, v64
	v_add_u32_e32 v64, 0xffffff36, v173
	s_nop 0
	v_cndmask_b32_e32 v85, v196, v85, vcc
	v_cmp_gt_u32_e32 vcc, s0, v64
	v_add_u32_e32 v64, 0xffffff16, v173
	s_nop 0
	v_cndmask_b32_e32 v102, v196, v102, vcc
	v_cmp_gt_u32_e32 vcc, s0, v64
	v_add_u32_e32 v64, 0xffffff35, v173
	s_nop 0
	v_cndmask_b32_e32 v86, v196, v86, vcc
	v_cmp_gt_u32_e32 vcc, s0, v64
	v_add_u32_e32 v64, 0xffffff15, v173
	s_nop 0
	v_cndmask_b32_e32 v103, v196, v103, vcc
	v_cmp_gt_u32_e32 vcc, s0, v64
	v_add_u32_e32 v64, 0xffffff30, v173
	s_nop 0
	v_cndmask_b32_e32 v87, v196, v87, vcc
	v_cmp_gt_u32_e32 vcc, s0, v64
	v_add_u32_e32 v64, 0xffffff10, v173
	s_nop 0
	v_cndmask_b32_e32 v104, v196, v104, vcc
	v_cmp_gt_u32_e32 vcc, s0, v64
	v_add_u32_e32 v64, 0xffffff2f, v173
	s_nop 0
	v_cndmask_b32_e32 v88, v196, v88, vcc
	v_cmp_gt_u32_e32 vcc, s0, v64
	v_add_u32_e32 v64, 0xffffff0f, v173
	s_nop 0
	v_cndmask_b32_e32 v105, v196, v105, vcc
	v_cmp_gt_u32_e32 vcc, s0, v64
	v_add_u32_e32 v64, 0xffffff2e, v173
	s_nop 0
	v_cndmask_b32_e32 v89, v196, v89, vcc
	v_cmp_gt_u32_e32 vcc, s0, v64
	v_add_u32_e32 v64, 0xffffff0e, v173
	s_nop 0
	v_cndmask_b32_e32 v106, v196, v106, vcc
	v_cmp_gt_u32_e32 vcc, s0, v64
	v_add_u32_e32 v64, 0xffffff2d, v173
	s_nop 0
	v_cndmask_b32_e32 v90, v196, v90, vcc
	v_cmp_gt_u32_e32 vcc, s0, v64
	v_add_u32_e32 v64, 0xffffff0d, v173
	s_nop 0
	v_cndmask_b32_e32 v107, v196, v107, vcc
	v_cmp_gt_u32_e32 vcc, s0, v64
	v_add_u32_e32 v64, 0xffffff28, v173
	s_nop 0
	v_cndmask_b32_e32 v91, v196, v91, vcc
	v_cmp_gt_u32_e32 vcc, s0, v64
	v_add_u32_e32 v64, 0xffffff08, v173
	s_nop 0
	v_cndmask_b32_e32 v108, v196, v108, vcc
	v_cmp_gt_u32_e32 vcc, s0, v64
	v_add_u32_e32 v64, 0xffffff27, v173
	s_nop 0
	v_cndmask_b32_e32 v92, v196, v92, vcc
	v_cmp_gt_u32_e32 vcc, s0, v64
	v_add_u32_e32 v64, 0xffffff07, v173
	s_nop 0
	v_cndmask_b32_e32 v109, v196, v109, vcc
	v_cmp_gt_u32_e32 vcc, s0, v64
	v_add_u32_e32 v64, 0xffffff26, v173
	s_nop 0
	v_cndmask_b32_e32 v93, v196, v93, vcc
	v_cmp_gt_u32_e32 vcc, s0, v64
	v_add_u32_e32 v64, 0xffffff06, v173
	s_nop 0
	v_cndmask_b32_e32 v110, v196, v110, vcc
	v_cmp_gt_u32_e32 vcc, s0, v64
	v_add_u32_e32 v64, 0xffffff25, v173
	s_nop 0
	v_cndmask_b32_e32 v94, v196, v94, vcc
	v_cmp_gt_u32_e32 vcc, s0, v64
	v_add_u32_e32 v64, 0xffffff05, v173
	s_nop 0
	v_cndmask_b32_e32 v111, v196, v111, vcc
	v_cmp_gt_u32_e32 vcc, s0, v64
	s_nop 1
	v_cndmask_b32_e32 v95, v196, v95, vcc

.LBB0_1133:
	v_exp_f32_e32 v64, v96
	v_exp_f32_e32 v120, v97
	v_exp_f32_e32 v65, v98
	v_exp_f32_e32 v99, v99
	v_exp_f32_e32 v66, v100
	v_add_f32_e32 v75, 0, v64
	v_exp_f32_e32 v98, v101
	v_add_f32_e32 v75, v120, v75
	v_exp_f32_e32 v67, v102
	v_add_f32_e32 v75, v65, v75
	v_exp_f32_e32 v97, v103
	v_add_f32_e32 v75, v99, v75
	v_exp_f32_e32 v68, v104
	v_add_f32_e32 v75, v66, v75
	v_exp_f32_e32 v96, v105
	v_add_f32_e32 v75, v98, v75
	v_exp_f32_e32 v69, v106
	v_add_f32_e32 v75, v67, v75
	v_exp_f32_e32 v79, v107
	v_add_f32_e32 v75, v97, v75
	v_exp_f32_e32 v70, v108
	v_add_f32_e32 v75, v68, v75
	v_exp_f32_e32 v78, v109
	v_add_f32_e32 v75, v96, v75
	v_exp_f32_e32 v71, v110
	v_add_f32_e32 v75, v69, v75
	v_exp_f32_e32 v77, v111
	v_add_f32_e32 v75, v79, v75
	v_exp_f32_e32 v80, v80
	v_add_f32_e32 v75, v70, v75
	v_exp_f32_e32 v81, v81
	v_add_f32_e32 v75, v78, v75
	v_exp_f32_e32 v82, v82
	v_add_f32_e32 v75, v71, v75
	v_exp_f32_e32 v83, v83
	v_add_f32_e32 v75, v77, v75
	v_exp_f32_e32 v84, v84
	v_add_f32_e32 v75, v80, v75
	v_exp_f32_e32 v85, v85
	v_add_f32_e32 v75, v81, v75
	v_exp_f32_e32 v86, v86
	v_add_f32_e32 v75, v82, v75
	v_exp_f32_e32 v87, v87
	v_add_f32_e32 v75, v83, v75
	v_exp_f32_e32 v88, v88
	v_add_f32_e32 v75, v84, v75
	v_exp_f32_e32 v89, v89
	v_add_f32_e32 v75, v85, v75
	v_exp_f32_e32 v90, v90
	v_add_f32_e32 v75, v86, v75
	v_exp_f32_e32 v91, v91
	v_add_f32_e32 v75, v87, v75
	v_exp_f32_e32 v92, v92
	v_add_f32_e32 v75, v88, v75
	v_exp_f32_e32 v93, v93
	v_add_f32_e32 v75, v89, v75
	v_exp_f32_e32 v94, v94
	v_add_f32_e32 v75, v90, v75
	v_exp_f32_e32 v95, v95
	v_add_f32_e32 v75, v91, v75
	v_add_f32_e32 v75, v92, v75
	v_add_f32_e32 v75, v93, v75
	v_add_f32_e32 v75, v94, v75
	v_add_f32_e32 v75, v95, v75
	v_mov_b32_e32 v76, v75
	s_nop 1
	v_permlane32_swap_b32_e32 v75, v76
	v_cvt_pk_bf16_f32 v64, v64, v120
	v_cvt_pk_bf16_f32 v65, v65, v99
	v_cvt_pk_bf16_f32 v66, v66, v98
	v_cvt_pk_bf16_f32 v67, v67, v97
	v_cvt_pk_bf16_f32 v68, v68, v96
	v_cvt_pk_bf16_f32 v69, v69, v79
	v_cvt_pk_bf16_f32 v70, v70, v78
	v_cvt_pk_bf16_f32 v71, v71, v77
	v_cvt_pk_bf16_f32 v78, v80, v81
	v_cvt_pk_bf16_f32 v79, v82, v83
	v_cvt_pk_bf16_f32 v80, v84, v85
	v_cvt_pk_bf16_f32 v81, v86, v87
	v_cvt_pk_bf16_f32 v82, v88, v89
	v_cvt_pk_bf16_f32 v83, v90, v91
	v_cvt_pk_bf16_f32 v84, v92, v93
	v_cvt_pk_bf16_f32 v85, v94, v95
	s_nop 0
	v_permlane32_swap_b32_e32 v64, v66
	v_permlane32_swap_b32_e32 v65, v67
	v_permlane32_swap_b32_e32 v68, v70
	v_permlane32_swap_b32_e32 v69, v71
	v_permlane32_swap_b32_e32 v78, v80
	v_permlane32_swap_b32_e32 v79, v81
	v_permlane32_swap_b32_e32 v82, v84
	v_permlane32_swap_b32_e32 v83, v85
	ds_read_b64_tr_b16 v[86:87], v175 offset:0x4000
	ds_read_b64_tr_b16 v[88:89], v175 offset:0x4800
	ds_read_b64_tr_b16 v[90:91], v175 offset:0x5000
	ds_read_b64_tr_b16 v[92:93], v175 offset:0x5800
	ds_read_b64_tr_b16 v[94:95], v175 offset:0x6000
	ds_read_b64_tr_b16 v[96:97], v175 offset:0x6800
	ds_read_b64_tr_b16 v[98:99], v175 offset:0x7000
	ds_read_b64_tr_b16 v[100:101], v175 offset:0x7800
	s_waitcnt lgkmcnt(0)
	s_nop 0
	v_mfma_f32_32x32x16_bf16 v[0:15], v[64:67], v[86:89], v[0:15]
	ds_read_b64_tr_b16 v[86:87], v175 offset:0x4200
	ds_read_b64_tr_b16 v[88:89], v175 offset:0x4a00
	v_mfma_f32_32x32x16_bf16 v[0:15], v[68:71], v[90:93], v[0:15]
	ds_read_b64_tr_b16 v[90:91], v175 offset:0x5200
	ds_read_b64_tr_b16 v[92:93], v175 offset:0x5a00
	v_mfma_f32_32x32x16_bf16 v[0:15], v[78:81], v[94:97], v[0:15]
	ds_read_b64_tr_b16 v[94:95], v175 offset:0x6200
	ds_read_b64_tr_b16 v[96:97], v175 offset:0x6a00
	v_mfma_f32_32x32x16_bf16 v[0:15], v[82:85], v[98:101], v[0:15]
	ds_read_b64_tr_b16 v[98:99], v175 offset:0x7200
	ds_read_b64_tr_b16 v[100:101], v175 offset:0x7a00
	s_waitcnt lgkmcnt(0)
	v_mfma_f32_32x32x16_bf16 v[16:31], v[64:67], v[86:89], v[16:31]
	ds_read_b64_tr_b16 v[86:87], v175 offset:0x4400
	ds_read_b64_tr_b16 v[88:89], v175 offset:0x4c00
	v_mfma_f32_32x32x16_bf16 v[16:31], v[68:71], v[90:93], v[16:31]
	ds_read_b64_tr_b16 v[90:91], v175 offset:0x5400
	ds_read_b64_tr_b16 v[92:93], v175 offset:0x5c00
	v_mfma_f32_32x32x16_bf16 v[16:31], v[78:81], v[94:97], v[16:31]
	ds_read_b64_tr_b16 v[94:95], v175 offset:0x6400
	ds_read_b64_tr_b16 v[96:97], v175 offset:0x6c00
	v_mfma_f32_32x32x16_bf16 v[16:31], v[82:85], v[98:101], v[16:31]
	ds_read_b64_tr_b16 v[98:99], v175 offset:0x7400
	ds_read_b64_tr_b16 v[100:101], v175 offset:0x7c00
	s_waitcnt lgkmcnt(0)
	v_mfma_f32_32x32x16_bf16 v[32:47], v[64:67], v[86:89], v[32:47]
	ds_read_b64_tr_b16 v[86:87], v175 offset:0x4600
	ds_read_b64_tr_b16 v[88:89], v175 offset:0x4e00
	v_mfma_f32_32x32x16_bf16 v[32:47], v[68:71], v[90:93], v[32:47]
	ds_read_b64_tr_b16 v[90:91], v175 offset:0x5600
	ds_read_b64_tr_b16 v[92:93], v175 offset:0x5e00
	v_mfma_f32_32x32x16_bf16 v[32:47], v[78:81], v[94:97], v[32:47]
	ds_read_b64_tr_b16 v[94:95], v175 offset:0x6600
	ds_read_b64_tr_b16 v[96:97], v175 offset:0x6e00
	v_mfma_f32_32x32x16_bf16 v[32:47], v[82:85], v[98:101], v[32:47]
	ds_read_b64_tr_b16 v[98:99], v175 offset:0x7600
	ds_read_b64_tr_b16 v[100:101], v175 offset:0x7e00
	s_waitcnt lgkmcnt(0)
	v_mfma_f32_32x32x16_bf16 v[48:63], v[64:67], v[86:89], v[48:63]
	v_mfma_f32_32x32x16_bf16 v[48:63], v[68:71], v[90:93], v[48:63]
	v_mfma_f32_32x32x16_bf16 v[48:63], v[78:81], v[94:97], v[48:63]
	v_mfma_f32_32x32x16_bf16 v[48:63], v[82:85], v[98:101], v[48:63]
	s_waitcnt vmcnt(8)
	s_waitcnt vmcnt(0)
	ds_write_b128 v174, v[112:115] offset:32768
	ds_write_b128 v174, v[116:119] offset:40960
	s_and_saveexec_b64 s[4:5], s[6:7]
	s_cbranch_execz .LBB0_1135
	v_add_f32_e32 v64, v176, v177
	v_add_f32_e32 v64, v172, v64
	v_add_f32_e32 v65, v187, v188
	v_fmac_f32_e32 v65, v64, v182
	v_add_f32_e32 v64, v72, v73
	v_fmac_f32_e32 v64, v65, v199
	v_add_f32_e32 v65, v75, v76
	v_fmac_f32_e32 v65, v64, v74
	ds_write_b32 v184, v65

.LBB0_1267:
	s_setprio 0
	v_readlane_b32 s52, v254, 1
	v_readlane_b32 s54, v254, 3
	v_readlane_b32 s55, v254, 4
	s_mov_b64 s[4:5], s[54:55]
	s_waitcnt vmcnt(0)
	v_readlane_b32 s0, v254, 8
	v_readlane_b32 s1, v254, 9
	v_readlane_b32 s56, v254, 58
	v_readlane_b32 s58, v255, 2
	v_readlane_b32 s60, v255, 6
	v_readlane_b32 s53, v254, 2
	s_and_b64 vcc, exec, s[0:1]
	v_readlane_b32 s57, v254, 59
	v_readlane_b32 s59, v255, 3
	v_readlane_b32 s61, v255, 7
	v_readlane_b32 s62, v254, 61
	v_readlane_b32 s63, v254, 60
	s_barrier
	s_cbranch_vccnz .LBB0_1313
	v_mbcnt_lo_u32_b32 v0, -1, 0
	v_mbcnt_hi_u32_b32 v0, -1, v0
	s_nop 0
	v_cmp_eq_u32_e32 vcc, 0, v0
	s_and_saveexec_b64 s[40:41], vcc
	s_cbranch_execz .LBB0_1312
	s_add_i32 s1, 0, 0x25ff0
	v_mov_b32_e32 v0, s1
	s_getreg_b32 s0, hwreg(HW_REG_XCC_ID, 0, 4)
	s_waitcnt vmcnt(0) expcnt(0) lgkmcnt(0)
	ds_read_b32 v2, v0
	s_add_i32 s1, 0, 0x25ff4
	v_mov_b32_e32 v0, s1
	ds_read_b32 v0, v0
	s_and_b32 s0, s0, 15
	s_waitcnt lgkmcnt(1)
	v_cmp_ne_u32_e32 vcc, 0, v2
	s_cbranch_vccnz .LBB0_1283
	s_add_u32 s6, s4, 0x100200
	s_addc_u32 s7, s5, 0
	s_add_u32 s10, s4, 0x100400
	s_addc_u32 s11, s5, 0
	s_add_u32 s12, s4, 0x100500
	s_addc_u32 s13, s5, 0
	s_add_u32 s14, s4, 0x100600
	s_addc_u32 s15, s5, 0
	s_add_u32 s16, s4, 0x100700
	s_addc_u32 s17, s5, 0
	s_add_u32 s18, s4, 0x100800
	s_addc_u32 s19, s5, 0
	s_add_u32 s20, s4, 0x100900
	s_addc_u32 s21, s5, 0
	s_add_u32 s22, s4, 0x100a00
	s_addc_u32 s23, s5, 0
	s_add_u32 s24, s4, 0x100b00
	s_addc_u32 s25, s5, 0
	s_add_u32 s26, s4, 0x100c00
	s_addc_u32 s27, s5, 0
	s_add_u32 s28, s4, 0x100d00
	s_addc_u32 s29, s5, 0
	s_add_u32 s30, s4, 0x100e00
	s_addc_u32 s31, s5, 0
	s_add_u32 s34, s4, 0x100f00
	s_addc_u32 s35, s5, 0
	s_add_u32 s36, s4, 0x101000
	s_addc_u32 s37, s5, 0
	s_add_u32 s38, s4, 0x101100
	s_addc_u32 s39, s5, 0
	s_add_u32 s42, s4, 0x101200
	s_addc_u32 s43, s5, 0
	v_readlane_b32 s1, v254, 0
	s_add_u32 s44, s4, 0x101300
	s_mul_i32 s1, s57, s1
	s_addc_u32 s45, s5, 0
	s_mul_i32 s1, s1, s56
	s_mov_b32 s2, 1
	s_mov_b64 s[8:9], 0
	s_waitcnt lgkmcnt(0)
	v_mov_b64_e32 v[0:1], s[10:11]
	v_mov_b64_e32 v[2:3], s[12:13]
	v_mov_b64_e32 v[4:5], s[14:15]
	v_mov_b64_e32 v[6:7], s[16:17]
	v_mov_b64_e32 v[8:9], s[18:19]
	v_mov_b64_e32 v[10:11], s[20:21]
	v_mov_b64_e32 v[12:13], s[22:23]
	v_mov_b64_e32 v[14:15], s[24:25]
	v_mov_b64_e32 v[16:17], s[26:27]
	v_mov_b64_e32 v[18:19], s[28:29]
	v_mov_b64_e32 v[20:21], s[30:31]
	v_mov_b64_e32 v[22:23], s[34:35]
	v_mov_b64_e32 v[24:25], s[36:37]
	v_mov_b64_e32 v[26:27], s[38:39]
	v_mov_b64_e32 v[28:29], s[42:43]
	v_mov_b64_e32 v[30:31], s[44:45]
	s_branch .LBB0_1273
